# EpiPair<0> epilogue: the row scales of tile i+1 are loaded and reduced during the epilogue of tile i and kept in 8 VGPRs across the K loop, so the epilogue math no longer waits on vmcnt (next tile's L
# baseline (speedup 1.0000x reference)
.LBB0_305:
	s_add_u32 s48, s48, 0x1ca40000
	s_addc_u32 s49, s49, 0
	s_lshl_b32 s3, s39, 5
	s_and_b32 s5, s3, 0x60
	s_add_i32 m0, s68, 0x18000
	v_lshl_add_u64 v[6:7], v[6:7], 0, s[26:27]
	s_lshl_b32 s4, s36, 13
	s_lshl_b32 s39, s5, 7
	s_waitcnt vmcnt(2)
	s_barrier
	global_load_lds_dwordx4 v[6:7], off
	v_lshl_add_u64 v[4:5], v[4:5], 0, s[26:27]
	s_add_i32 m0, s68, 0x1a000
	s_add_i32 s72, s68, 0x8000
	s_add_i32 s73, s68, 0xa000
	global_load_lds_dwordx4 v[4:5], off
	v_lshl_add_u64 v[0:1], v[0:1], 0, s[26:27]
	s_mov_b32 m0, s72
	s_add_u32 s50, s64, 0x40080
	global_load_lds_dwordx4 v[0:1], off
	v_lshl_add_u64 v[0:1], v[2:3], 0, s[26:27]
	s_mov_b32 m0, s73
	s_addc_u32 s51, s65, 0
	global_load_lds_dwordx4 v[0:1], off
	s_add_i32 m0, s68, 0x1c000
	v_lshl_add_u64 v[0:1], s[50:51], 0, v[144:145]
	global_load_lds_dwordx4 v[0:1], off
	v_lshl_add_u64 v[0:1], s[50:51], 0, v[128:129]
	s_add_i32 m0, s68, 0x1e000
	s_cmpk_lt_u32 s33, 0x100
	global_load_lds_dwordx4 v[0:1], off
	v_lshrrev_b32_e32 v1, 1, v8
	v_and_b32_e32 v1, 24, v1
	v_and_b32_e32 v0, 15, v8
	v_lshlrev_b32_e32 v2, 1, v1
	v_lshl_or_b32 v142, s36, 6, v0
	v_lshl_or_b32 v0, v0, 6, v2
	v_lshlrev_b32_e32 v2, 2, v8
	v_and_b32_e32 v2, 32, v2
	v_bitop3_b32 v3, v0, s4, v2 bitop3:0xde
	v_bitop3_b32 v143, v0, s39, v2 bitop3:0xde
	v_lshlrev_b32_e32 v0, 14, v13
	v_and_b32_e32 v0, 0xffff8000, v0
	v_or_b32_e32 v154, s5, v1
	v_lshl_add_u32 v0, v12, 11, v0
	v_and_b32_e32 v1, 1, v13
	v_lshl_or_b32 v0, v1, 6, v0
	v_lshl_add_u32 v134, v14, 1, v0
	v_lshlrev_b32_e32 v0, 14, v9
	v_and_b32_e32 v0, 0xffff8000, v0
	s_waitcnt vmcnt(6)
	v_lshl_add_u32 v0, v10, 11, v0
	v_and_b32_e32 v1, 1, v9
	v_lshl_or_b32 v0, v1, 6, v0
	s_sext_i32_i16 s3, s38
	s_cselect_b64 s[50:51], -1, 0
	v_mov_b32_e32 v135, v145
	v_lshl_add_u32 v136, v11, 1, v0
	v_mov_b32_e32 v137, v145
	s_mov_b32 s74, 0
	v_add_u32_e32 v155, 0, v3
	s_barrier
	v_lshl_add_u32 v96, s2, 8, v142
	v_ashrrev_i32_e32 v97, 31, v96
	v_lshl_add_u64 v[96:97], v[96:97], 4, s[48:49]
	global_load_dwordx4 v[64:67], v[96:97], off
	global_load_dwordx4 v[68:71], v[96:97], off offset:256
	global_load_dwordx4 v[72:75], v[96:97], off offset:512
	global_load_dwordx4 v[76:79], v[96:97], off offset:768
	global_load_dwordx4 v[80:83], v[96:97], off offset:2048
	global_load_dwordx4 v[84:87], v[96:97], off offset:2304
	global_load_dwordx4 v[88:91], v[96:97], off offset:2560
	global_load_dwordx4 v[92:95], v[96:97], off offset:2816
	s_waitcnt vmcnt(0)
	v_add_f32_e32 v64, v65, v64
	v_add_f32_e32 v68, v69, v68
	v_add_f32_e32 v72, v73, v72
	v_add_f32_e32 v76, v77, v76
	v_add_f32_e32 v80, v81, v80
	v_add_f32_e32 v84, v85, v84
	v_add_f32_e32 v88, v89, v88
	v_add_f32_e32 v92, v93, v92
	v_add_f32_e32 v66, v66, v67
	v_add_f32_e32 v70, v70, v71
	v_add_f32_e32 v74, v74, v75
	v_add_f32_e32 v78, v78, v79
	v_add_f32_e32 v82, v82, v83
	v_add_f32_e32 v86, v86, v87
	v_add_f32_e32 v90, v90, v91
	v_add_f32_e32 v94, v94, v95
	v_add_f32_e32 v64, v64, v66
	v_add_f32_e32 v68, v68, v70
	v_add_f32_e32 v72, v72, v74
	v_add_f32_e32 v76, v76, v78
	v_add_f32_e32 v80, v80, v82
	v_add_f32_e32 v84, v84, v86
	v_add_f32_e32 v88, v88, v90
	v_add_f32_e32 v92, v92, v94
	v_fmamk_f32 v64, v64, 0x3a800000, v184
	v_fmamk_f32 v68, v68, 0x3a800000, v184
	v_fmamk_f32 v72, v72, 0x3a800000, v184
	v_fmamk_f32 v76, v76, 0x3a800000, v184
	v_fmamk_f32 v80, v80, 0x3a800000, v184
	v_fmamk_f32 v84, v84, 0x3a800000, v184
	v_fmamk_f32 v88, v88, 0x3a800000, v184
	v_fmamk_f32 v92, v92, 0x3a800000, v184
	v_rsq_f32_e32 v202, v64
	v_rsq_f32_e32 v203, v68
	v_rsq_f32_e32 v248, v72
	v_rsq_f32_e32 v249, v76
	v_rsq_f32_e32 v250, v80
	v_rsq_f32_e32 v251, v84
	v_rsq_f32_e32 v252, v88
	v_rsq_f32_e32 v253, v92
	s_branch .LBB0_308

.LBB0_311:
	s_add_u32 s4, s62, 0xfffc0080
	s_addc_u32 s5, s63, -1
	s_add_i32 s84, 0, 0x10000
	s_cmp_eq_u32 s82, 12
	s_cselect_b32 s65, s33, s5
	s_cselect_b32 s64, s36, s4
	s_cselect_b32 s35, s53, s79
	s_cselect_b32 s34, s55, s75
	s_add_i32 s4, 0, 0x14000
	v_add_u32_e32 v164, s84, v143
	v_add_u32_e32 v180, s4, v143
	ds_read_b128 v[138:141], v164
	ds_read_b128 v[156:159], v164 offset:1024
	ds_read_b128 v[160:163], v164 offset:2048
	ds_read_b128 v[164:167], v164 offset:3072
	ds_read_b128 v[168:171], v180
	ds_read_b128 v[172:175], v180 offset:1024
	ds_read_b128 v[176:179], v180 offset:2048
	ds_read_b128 v[204:207], v180 offset:3072
	v_lshl_add_u64 v[180:181], s[62:63], 0, v[134:135]
	s_add_i32 m0, s68, 0xc000
	ds_read_b128 v[208:211], v155
	ds_read_b128 v[212:215], v155 offset:1024
	ds_read_b128 v[216:219], v155 offset:2048
	ds_read_b128 v[220:223], v155 offset:3072
	ds_read_b128 v[224:227], v155 offset:4096
	ds_read_b128 v[228:231], v155 offset:5120
	ds_read_b128 v[232:235], v155 offset:6144
	ds_read_b128 v[236:239], v155 offset:7168
	global_load_lds_dwordx4 v[180:181], off
	v_lshl_add_u64 v[180:181], s[62:63], 0, v[136:137]
	s_add_i32 m0, s68, 0xe000
	s_nop 0
	global_load_lds_dwordx4 v[180:181], off
	s_waitcnt vmcnt(8)
	s_waitcnt lgkmcnt(0)
	s_barrier
	s_setprio 1
	s_waitcnt lgkmcnt(0)
	v_mfma_f32_16x16x32_bf16 v[124:127], v[138:141], v[208:211], v[124:127]
	v_mfma_f32_16x16x32_bf16 v[120:123], v[160:163], v[208:211], v[120:123]
	v_mfma_f32_16x16x32_bf16 v[108:111], v[138:141], v[216:219], v[108:111]
	v_mfma_f32_16x16x32_bf16 v[104:107], v[160:163], v[216:219], v[104:107]
	v_mfma_f32_16x16x32_bf16 v[92:95], v[138:141], v[224:227], v[92:95]
	v_mfma_f32_16x16x32_bf16 v[88:91], v[160:163], v[224:227], v[88:91]
	v_mfma_f32_16x16x32_bf16 v[76:79], v[138:141], v[232:235], v[76:79]
	v_mfma_f32_16x16x32_bf16 v[72:75], v[160:163], v[232:235], v[72:75]
	v_mfma_f32_16x16x32_bf16 v[124:127], v[156:159], v[212:215], v[124:127]
	v_mfma_f32_16x16x32_bf16 v[120:123], v[164:167], v[212:215], v[120:123]
	v_mfma_f32_16x16x32_bf16 v[108:111], v[156:159], v[220:223], v[108:111]
	v_mfma_f32_16x16x32_bf16 v[104:107], v[164:167], v[220:223], v[104:107]
	v_mfma_f32_16x16x32_bf16 v[92:95], v[156:159], v[228:231], v[92:95]
	v_mfma_f32_16x16x32_bf16 v[88:91], v[164:167], v[228:231], v[88:91]
	v_mfma_f32_16x16x32_bf16 v[76:79], v[156:159], v[236:239], v[76:79]
	v_mfma_f32_16x16x32_bf16 v[72:75], v[164:167], v[236:239], v[72:75]
	s_setprio 0
	s_setprio 1
	v_mfma_f32_16x16x32_bf16 v[116:119], v[168:171], v[208:211], v[116:119]
	v_mfma_f32_16x16x32_bf16 v[112:115], v[176:179], v[208:211], v[112:115]
	v_mfma_f32_16x16x32_bf16 v[100:103], v[168:171], v[216:219], v[100:103]
	v_mfma_f32_16x16x32_bf16 v[96:99], v[176:179], v[216:219], v[96:99]
	v_mfma_f32_16x16x32_bf16 v[84:87], v[168:171], v[224:227], v[84:87]
	v_mfma_f32_16x16x32_bf16 v[80:83], v[176:179], v[224:227], v[80:83]
	v_mfma_f32_16x16x32_bf16 v[68:71], v[168:171], v[232:235], v[68:71]
	v_mfma_f32_16x16x32_bf16 v[64:67], v[176:179], v[232:235], v[64:67]
	v_mfma_f32_16x16x32_bf16 v[116:119], v[172:175], v[212:215], v[116:119]
	v_mfma_f32_16x16x32_bf16 v[112:115], v[204:207], v[212:215], v[112:115]
	v_mfma_f32_16x16x32_bf16 v[100:103], v[172:175], v[220:223], v[100:103]
	v_mfma_f32_16x16x32_bf16 v[96:99], v[204:207], v[220:223], v[96:99]
	v_mfma_f32_16x16x32_bf16 v[84:87], v[172:175], v[228:231], v[84:87]
	v_mfma_f32_16x16x32_bf16 v[80:83], v[204:207], v[228:231], v[80:83]
	v_mfma_f32_16x16x32_bf16 v[68:71], v[172:175], v[236:239], v[68:71]
	v_mfma_f32_16x16x32_bf16 v[64:67], v[204:207], v[236:239], v[64:67]
	s_setprio 0
	s_barrier
	s_add_i32 s5, s84, s28
	v_lshl_add_u64 v[180:181], s[34:35], 0, v[144:145]
	s_mov_b32 m0, s5
	ds_read_b128 v[208:211], v155 offset:16384
	ds_read_b128 v[212:215], v155 offset:17408
	ds_read_b128 v[216:219], v155 offset:18432
	ds_read_b128 v[220:223], v155 offset:19456
	ds_read_b128 v[224:227], v155 offset:20480
	ds_read_b128 v[228:231], v155 offset:21504
	ds_read_b128 v[232:235], v155 offset:22528
	ds_read_b128 v[236:239], v155 offset:23552
	global_load_lds_dwordx4 v[180:181], off
	s_add_i32 m0, s5, 0x2000
	s_add_u32 s88, s34, 0x40000
	v_lshl_add_u64 v[240:241], s[34:35], 0, v[128:129]
	s_addc_u32 s89, s35, 0
	s_add_i32 s4, s4, s28
	global_load_lds_dwordx4 v[240:241], off
	v_lshl_add_u64 v[242:243], s[88:89], 0, v[144:145]
	s_mov_b32 m0, s4
	v_lshl_add_u64 v[244:245], s[64:65], 0, v[130:131]
	global_load_lds_dwordx4 v[242:243], off
	v_lshl_add_u64 v[242:243], s[88:89], 0, v[128:129]
	s_add_i32 m0, s4, 0x2000
	s_nop 0
	global_load_lds_dwordx4 v[242:243], off
	v_lshl_add_u64 v[242:243], s[64:65], 0, v[132:133]
	s_mov_b32 m0, s68
	s_nop 0
	global_load_lds_dwordx4 v[242:243], off
	s_mov_b32 m0, s69
	s_nop 0
	global_load_lds_dwordx4 v[244:245], off
	s_waitcnt vmcnt(8)
	s_waitcnt lgkmcnt(0)
	s_barrier
	s_setprio 1
	s_waitcnt lgkmcnt(0)
	v_mfma_f32_16x16x32_bf16 v[60:63], v[138:141], v[208:211], v[60:63]
	v_mfma_f32_16x16x32_bf16 v[56:59], v[160:163], v[208:211], v[56:59]
	v_mfma_f32_16x16x32_bf16 v[44:47], v[138:141], v[216:219], v[44:47]
	v_mfma_f32_16x16x32_bf16 v[40:43], v[160:163], v[216:219], v[40:43]
	v_mfma_f32_16x16x32_bf16 v[28:31], v[138:141], v[224:227], v[28:31]
	v_mfma_f32_16x16x32_bf16 v[24:27], v[160:163], v[224:227], v[24:27]
	v_mfma_f32_16x16x32_bf16 v[12:15], v[138:141], v[232:235], v[12:15]
	v_mfma_f32_16x16x32_bf16 v[8:11], v[160:163], v[232:235], v[8:11]
	v_mfma_f32_16x16x32_bf16 v[60:63], v[156:159], v[212:215], v[60:63]
	v_mfma_f32_16x16x32_bf16 v[56:59], v[164:167], v[212:215], v[56:59]
	v_mfma_f32_16x16x32_bf16 v[44:47], v[156:159], v[220:223], v[44:47]
	v_mfma_f32_16x16x32_bf16 v[40:43], v[164:167], v[220:223], v[40:43]
	v_mfma_f32_16x16x32_bf16 v[28:31], v[156:159], v[228:231], v[28:31]
	v_mfma_f32_16x16x32_bf16 v[24:27], v[164:167], v[228:231], v[24:27]
	v_mfma_f32_16x16x32_bf16 v[12:15], v[156:159], v[236:239], v[12:15]
	v_mfma_f32_16x16x32_bf16 v[8:11], v[164:167], v[236:239], v[8:11]
	s_setprio 0
	s_setprio 1
	v_mfma_f32_16x16x32_bf16 v[52:55], v[168:171], v[208:211], v[52:55]
	v_mfma_f32_16x16x32_bf16 v[48:51], v[176:179], v[208:211], v[48:51]
	v_mfma_f32_16x16x32_bf16 v[36:39], v[168:171], v[216:219], v[36:39]
	v_mfma_f32_16x16x32_bf16 v[32:35], v[176:179], v[216:219], v[32:35]
	v_mfma_f32_16x16x32_bf16 v[20:23], v[168:171], v[224:227], v[20:23]
	v_mfma_f32_16x16x32_bf16 v[16:19], v[176:179], v[224:227], v[16:19]
	v_mfma_f32_16x16x32_bf16 v[4:7], v[168:171], v[232:235], v[4:7]
	v_mfma_f32_16x16x32_bf16 v[0:3], v[176:179], v[232:235], v[0:3]
	v_mfma_f32_16x16x32_bf16 v[52:55], v[172:175], v[212:215], v[52:55]
	v_mfma_f32_16x16x32_bf16 v[48:51], v[204:207], v[212:215], v[48:51]
	v_mfma_f32_16x16x32_bf16 v[36:39], v[172:175], v[220:223], v[36:39]
	v_mfma_f32_16x16x32_bf16 v[32:35], v[204:207], v[220:223], v[32:35]
	v_mfma_f32_16x16x32_bf16 v[20:23], v[172:175], v[228:231], v[20:23]
	v_mfma_f32_16x16x32_bf16 v[16:19], v[204:207], v[228:231], v[16:19]
	v_mfma_f32_16x16x32_bf16 v[4:7], v[172:175], v[236:239], v[4:7]
	v_mfma_f32_16x16x32_bf16 v[0:3], v[204:207], v[236:239], v[0:3]
	s_setprio 0
	s_barrier
	s_add_i32 s4, 0, 0x18000
	s_add_i32 s5, 0, 0x1c000
	v_add_u32_e32 v164, s4, v143
	v_add_u32_e32 v246, s5, v143
	ds_read_b128 v[138:141], v164
	ds_read_b128 v[156:159], v164 offset:1024
	ds_read_b128 v[160:163], v164 offset:2048
	ds_read_b128 v[164:167], v164 offset:3072
	ds_read_b128 v[168:171], v246
	ds_read_b128 v[172:175], v246 offset:1024
	ds_read_b128 v[176:179], v246 offset:2048
	ds_read_b128 v[204:207], v246 offset:3072
	s_add_u32 s64, s64, 0x40000
	s_addc_u32 s65, s65, 0
	s_mov_b32 m0, s70
	v_lshl_add_u64 v[246:247], s[64:65], 0, v[132:133]
	ds_read_b128 v[208:211], v155 offset:32768
	ds_read_b128 v[212:215], v155 offset:33792
	ds_read_b128 v[216:219], v155 offset:34816
	ds_read_b128 v[220:223], v155 offset:35840
	ds_read_b128 v[224:227], v155 offset:36864
	ds_read_b128 v[228:231], v155 offset:37888
	ds_read_b128 v[232:235], v155 offset:38912
	ds_read_b128 v[236:239], v155 offset:39936
	global_load_lds_dwordx4 v[246:247], off
	v_lshl_add_u64 v[246:247], s[64:65], 0, v[130:131]
	s_mov_b32 m0, s71
	s_nop 0
	global_load_lds_dwordx4 v[246:247], off
	s_waitcnt vmcnt(8)
	s_waitcnt lgkmcnt(0)
	s_barrier
	s_setprio 1
	s_waitcnt lgkmcnt(0)
	v_mfma_f32_16x16x32_bf16 v[124:127], v[138:141], v[208:211], v[124:127]
	v_mfma_f32_16x16x32_bf16 v[120:123], v[160:163], v[208:211], v[120:123]
	v_mfma_f32_16x16x32_bf16 v[108:111], v[138:141], v[216:219], v[108:111]
	v_mfma_f32_16x16x32_bf16 v[104:107], v[160:163], v[216:219], v[104:107]
	v_mfma_f32_16x16x32_bf16 v[92:95], v[138:141], v[224:227], v[92:95]
	v_mfma_f32_16x16x32_bf16 v[88:91], v[160:163], v[224:227], v[88:91]
	v_mfma_f32_16x16x32_bf16 v[76:79], v[138:141], v[232:235], v[76:79]
	v_mfma_f32_16x16x32_bf16 v[72:75], v[160:163], v[232:235], v[72:75]
	v_mfma_f32_16x16x32_bf16 v[124:127], v[156:159], v[212:215], v[124:127]
	v_mfma_f32_16x16x32_bf16 v[120:123], v[164:167], v[212:215], v[120:123]
	v_mfma_f32_16x16x32_bf16 v[108:111], v[156:159], v[220:223], v[108:111]
	v_mfma_f32_16x16x32_bf16 v[104:107], v[164:167], v[220:223], v[104:107]
	v_mfma_f32_16x16x32_bf16 v[92:95], v[156:159], v[228:231], v[92:95]
	v_mfma_f32_16x16x32_bf16 v[88:91], v[164:167], v[228:231], v[88:91]
	v_mfma_f32_16x16x32_bf16 v[76:79], v[156:159], v[236:239], v[76:79]
	v_mfma_f32_16x16x32_bf16 v[72:75], v[164:167], v[236:239], v[72:75]
	s_setprio 0
	s_setprio 1
	v_mfma_f32_16x16x32_bf16 v[116:119], v[168:171], v[208:211], v[116:119]
	v_mfma_f32_16x16x32_bf16 v[112:115], v[176:179], v[208:211], v[112:115]
	v_mfma_f32_16x16x32_bf16 v[100:103], v[168:171], v[216:219], v[100:103]
	v_mfma_f32_16x16x32_bf16 v[96:99], v[176:179], v[216:219], v[96:99]
	v_mfma_f32_16x16x32_bf16 v[84:87], v[168:171], v[224:227], v[84:87]
	v_mfma_f32_16x16x32_bf16 v[80:83], v[176:179], v[224:227], v[80:83]
	v_mfma_f32_16x16x32_bf16 v[68:71], v[168:171], v[232:235], v[68:71]
	v_mfma_f32_16x16x32_bf16 v[64:67], v[176:179], v[232:235], v[64:67]
	v_mfma_f32_16x16x32_bf16 v[116:119], v[172:175], v[212:215], v[116:119]
	v_mfma_f32_16x16x32_bf16 v[112:115], v[204:207], v[212:215], v[112:115]
	v_mfma_f32_16x16x32_bf16 v[100:103], v[172:175], v[220:223], v[100:103]
	v_mfma_f32_16x16x32_bf16 v[96:99], v[204:207], v[220:223], v[96:99]
	v_mfma_f32_16x16x32_bf16 v[84:87], v[172:175], v[228:231], v[84:87]
	v_mfma_f32_16x16x32_bf16 v[80:83], v[204:207], v[228:231], v[80:83]
	v_mfma_f32_16x16x32_bf16 v[68:71], v[172:175], v[236:239], v[68:71]
	v_mfma_f32_16x16x32_bf16 v[64:67], v[204:207], v[236:239], v[64:67]
	s_setprio 0
	s_barrier
	s_add_i32 s4, s4, s28
	v_lshl_add_u64 v[180:181], v[180:181], 0, s[26:27]
	s_mov_b32 m0, s4
	ds_read_b128 v[208:211], v155 offset:49152
	ds_read_b128 v[212:215], v155 offset:50176
	ds_read_b128 v[216:219], v155 offset:51200
	ds_read_b128 v[220:223], v155 offset:52224
	ds_read_b128 v[224:227], v155 offset:53248
	ds_read_b128 v[228:231], v155 offset:54272
	ds_read_b128 v[232:235], v155 offset:55296
	ds_read_b128 v[236:239], v155 offset:56320
	global_load_lds_dwordx4 v[180:181], off
	s_add_i32 m0, s4, 0x2000
	s_add_u32 s34, s34, 0x40080
	v_lshl_add_u64 v[180:181], v[240:241], 0, s[26:27]
	s_addc_u32 s35, s35, 0
	s_add_i32 s4, s5, s28
	global_load_lds_dwordx4 v[180:181], off
	v_lshl_add_u64 v[180:181], s[34:35], 0, v[144:145]
	s_mov_b32 m0, s4
	s_nop 0
	global_load_lds_dwordx4 v[180:181], off
	v_lshl_add_u64 v[180:181], s[34:35], 0, v[128:129]
	s_add_i32 m0, s4, 0x2000
	s_nop 0
	global_load_lds_dwordx4 v[180:181], off
	v_lshl_add_u64 v[180:181], v[242:243], 0, s[26:27]
	s_mov_b32 m0, s72
	s_nop 0
	global_load_lds_dwordx4 v[180:181], off
	v_lshl_add_u64 v[180:181], v[244:245], 0, s[26:27]
	s_mov_b32 m0, s73
	s_nop 0
	global_load_lds_dwordx4 v[180:181], off
	s_waitcnt vmcnt(8)
	s_waitcnt lgkmcnt(0)
	s_barrier
	s_setprio 1
	s_waitcnt lgkmcnt(0)
	v_mfma_f32_16x16x32_bf16 v[60:63], v[138:141], v[208:211], v[60:63]
	v_mfma_f32_16x16x32_bf16 v[56:59], v[160:163], v[208:211], v[56:59]
	v_mfma_f32_16x16x32_bf16 v[44:47], v[138:141], v[216:219], v[44:47]
	v_mfma_f32_16x16x32_bf16 v[40:43], v[160:163], v[216:219], v[40:43]
	v_mfma_f32_16x16x32_bf16 v[28:31], v[138:141], v[224:227], v[28:31]
	v_mfma_f32_16x16x32_bf16 v[24:27], v[160:163], v[224:227], v[24:27]
	v_mfma_f32_16x16x32_bf16 v[12:15], v[138:141], v[232:235], v[12:15]
	v_mfma_f32_16x16x32_bf16 v[8:11], v[160:163], v[232:235], v[8:11]
	v_mfma_f32_16x16x32_bf16 v[60:63], v[156:159], v[212:215], v[60:63]
	v_mfma_f32_16x16x32_bf16 v[56:59], v[164:167], v[212:215], v[56:59]
	v_mfma_f32_16x16x32_bf16 v[44:47], v[156:159], v[220:223], v[44:47]
	v_mfma_f32_16x16x32_bf16 v[40:43], v[164:167], v[220:223], v[40:43]
	v_mfma_f32_16x16x32_bf16 v[28:31], v[156:159], v[228:231], v[28:31]
	v_mfma_f32_16x16x32_bf16 v[24:27], v[164:167], v[228:231], v[24:27]
	v_mfma_f32_16x16x32_bf16 v[12:15], v[156:159], v[236:239], v[12:15]
	v_mfma_f32_16x16x32_bf16 v[8:11], v[164:167], v[236:239], v[8:11]
	s_setprio 0
	s_setprio 1
	v_mfma_f32_16x16x32_bf16 v[52:55], v[168:171], v[208:211], v[52:55]
	v_mfma_f32_16x16x32_bf16 v[48:51], v[176:179], v[208:211], v[48:51]
	v_mfma_f32_16x16x32_bf16 v[36:39], v[168:171], v[216:219], v[36:39]
	v_mfma_f32_16x16x32_bf16 v[32:35], v[176:179], v[216:219], v[32:35]
	v_mfma_f32_16x16x32_bf16 v[20:23], v[168:171], v[224:227], v[20:23]
	v_mfma_f32_16x16x32_bf16 v[16:19], v[176:179], v[224:227], v[16:19]
	v_mfma_f32_16x16x32_bf16 v[4:7], v[168:171], v[232:235], v[4:7]
	v_mfma_f32_16x16x32_bf16 v[0:3], v[176:179], v[232:235], v[0:3]
	v_mfma_f32_16x16x32_bf16 v[52:55], v[172:175], v[212:215], v[52:55]
	v_mfma_f32_16x16x32_bf16 v[48:51], v[204:207], v[212:215], v[48:51]
	v_mfma_f32_16x16x32_bf16 v[36:39], v[172:175], v[220:223], v[36:39]
	v_mfma_f32_16x16x32_bf16 v[32:35], v[204:207], v[220:223], v[32:35]
	v_mfma_f32_16x16x32_bf16 v[20:23], v[172:175], v[228:231], v[20:23]
	v_mfma_f32_16x16x32_bf16 v[16:19], v[204:207], v[228:231], v[16:19]
	v_mfma_f32_16x16x32_bf16 v[4:7], v[172:175], v[236:239], v[4:7]
	v_mfma_f32_16x16x32_bf16 v[0:3], v[204:207], v[236:239], v[0:3]
	s_setprio 0
	s_barrier
	s_add_i32 s82, s82, 2
	s_add_u32 s62, s62, 0x100
	s_addc_u32 s63, s63, 0
	s_add_u32 s75, s75, 0x100
	s_addc_u32 s79, s79, 0
	s_cmp_gt_u32 s82, 13
	s_cbranch_scc0 .LBB0_311
	s_and_b64 vcc, s[38:39], exec
	s_cselect_b32 s4, s54, s2
	v_lshl_add_u32 v178, s4, 8, v142
	v_ashrrev_i32_e32 v179, 31, v178
	v_lshl_add_u64 v[178:179], v[178:179], 4, s[48:49]
	global_load_dwordx4 v[208:211], v[178:179], off
	global_load_dwordx4 v[212:215], v[178:179], off offset:256
	global_load_dwordx4 v[216:219], v[178:179], off offset:512
	global_load_dwordx4 v[220:223], v[178:179], off offset:768
	global_load_dwordx4 v[224:227], v[178:179], off offset:2048
	global_load_dwordx4 v[228:231], v[178:179], off offset:2304
	global_load_dwordx4 v[232:235], v[178:179], off offset:2560
	global_load_dwordx4 v[236:239], v[178:179], off offset:2816
	s_and_b64 vcc, exec, s[50:51]
	s_cbranch_vccz .LBB0_314
	s_barrier
.LBB0_314:
	v_lshl_add_u32 v140, s2, 8, v142
	v_lshl_or_b32 v164, s3, 8, v154
	v_mov_b32_e32 v176, 0xbfb8aa3b
	v_ashrrev_i32_e32 v164, 1, v164
	v_ashrrev_i32_e32 v165, 31, v164
	v_mov_b32_e32 v177, 0xbfb8aa3b
	v_lshl_add_u64 v[138:139], v[164:165], 1, s[46:47]
	v_pk_mul_f32 v[124:125], v[124:125], v[202:203] op_sel_hi:[1,0]
	v_pk_mul_f32 v[126:127], v[126:127], v[202:203] op_sel_hi:[1,0]
	v_pk_mul_f32 v[116:117], v[116:117], v[202:203] op_sel_hi:[1,0]
	v_pk_mul_f32 v[118:119], v[118:119], v[202:203] op_sel_hi:[1,0]
	v_pk_mul_f32 v[120:121], v[120:121], v[202:203] op_sel_hi:[1,0]
	v_pk_mul_f32 v[122:123], v[122:123], v[202:203] op_sel_hi:[1,0]
	v_pk_mul_f32 v[112:113], v[112:113], v[202:203] op_sel_hi:[1,0]
	v_pk_mul_f32 v[114:115], v[114:115], v[202:203] op_sel_hi:[1,0]
	v_pk_mul_f32 v[160:161], v[124:125], v[176:177] op_sel_hi:[1,0]
	v_pk_mul_f32 v[162:163], v[126:127], v[176:177] op_sel_hi:[1,0]
	v_pk_mul_f32 v[164:165], v[116:117], v[176:177] op_sel_hi:[1,0]
	v_pk_mul_f32 v[166:167], v[118:119], v[176:177] op_sel_hi:[1,0]
	v_mad_i64_i32 v[156:157], s[2:3], v140, s78, v[138:139]
	v_exp_f32_e32 v160, v160
	v_exp_f32_e32 v161, v161
	v_exp_f32_e32 v162, v162
	v_exp_f32_e32 v163, v163
	v_exp_f32_e32 v164, v164
	v_exp_f32_e32 v165, v165
	v_exp_f32_e32 v166, v166
	v_exp_f32_e32 v167, v167
	v_pk_add_f32 v[160:161], v[160:161], 1.0 op_sel_hi:[1,0]
	v_pk_add_f32 v[162:163], v[162:163], 1.0 op_sel_hi:[1,0]
	v_pk_add_f32 v[164:165], v[164:165], 1.0 op_sel_hi:[1,0]
	v_pk_add_f32 v[166:167], v[166:167], 1.0 op_sel_hi:[1,0]
	v_rcp_f32_e32 v160, v160
	v_rcp_f32_e32 v161, v161
	v_rcp_f32_e32 v162, v162
	v_rcp_f32_e32 v163, v163
	v_rcp_f32_e32 v164, v164
	v_rcp_f32_e32 v165, v165
	v_rcp_f32_e32 v166, v166
	v_rcp_f32_e32 v167, v167
	v_pk_mul_f32 v[160:161], v[124:125], v[160:161]
	v_pk_mul_f32 v[162:163], v[126:127], v[162:163]
	v_pk_mul_f32 v[164:165], v[116:117], v[164:165]
	v_pk_mul_f32 v[166:167], v[118:119], v[166:167]
	v_pk_mul_f32 v[160:161], v[120:121], v[160:161]
	v_pk_mul_f32 v[162:163], v[122:123], v[162:163]
	v_pk_mul_f32 v[164:165], v[112:113], v[164:165]
	v_pk_mul_f32 v[166:167], v[114:115], v[166:167]
	v_cvt_pk_bf16_f32 v168, v160, v161
	v_cvt_pk_bf16_f32 v169, v162, v163
	v_cvt_pk_bf16_f32 v170, v164, v165
	v_cvt_pk_bf16_f32 v171, v166, v167
	global_store_dwordx2 v[156:157], v[168:169], off
	global_store_dwordx2 v[156:157], v[170:171], off offset:128
	v_pk_mul_f32 v[108:109], v[108:109], v[202:203] op_sel:[0,1] op_sel_hi:[1,1]
	v_pk_mul_f32 v[110:111], v[110:111], v[202:203] op_sel:[0,1] op_sel_hi:[1,1]
	v_pk_mul_f32 v[100:101], v[100:101], v[202:203] op_sel:[0,1] op_sel_hi:[1,1]
	v_pk_mul_f32 v[102:103], v[102:103], v[202:203] op_sel:[0,1] op_sel_hi:[1,1]
	v_pk_mul_f32 v[104:105], v[104:105], v[202:203] op_sel:[0,1] op_sel_hi:[1,1]
	v_pk_mul_f32 v[106:107], v[106:107], v[202:203] op_sel:[0,1] op_sel_hi:[1,1]
	v_pk_mul_f32 v[96:97], v[96:97], v[202:203] op_sel:[0,1] op_sel_hi:[1,1]
	v_pk_mul_f32 v[98:99], v[98:99], v[202:203] op_sel:[0,1] op_sel_hi:[1,1]
	v_add_u32_e32 v141, 0x10, v140
	v_pk_mul_f32 v[160:161], v[108:109], v[176:177] op_sel_hi:[1,0]
	v_pk_mul_f32 v[162:163], v[110:111], v[176:177] op_sel_hi:[1,0]
	v_pk_mul_f32 v[164:165], v[100:101], v[176:177] op_sel_hi:[1,0]
	v_pk_mul_f32 v[166:167], v[102:103], v[176:177] op_sel_hi:[1,0]
	v_mad_i64_i32 v[158:159], s[2:3], v141, s78, v[138:139]
	v_exp_f32_e32 v160, v160
	v_exp_f32_e32 v161, v161
	v_exp_f32_e32 v162, v162
	v_exp_f32_e32 v163, v163
	v_exp_f32_e32 v164, v164
	v_exp_f32_e32 v165, v165
	v_exp_f32_e32 v166, v166
	v_exp_f32_e32 v167, v167
	v_pk_add_f32 v[160:161], v[160:161], 1.0 op_sel_hi:[1,0]
	v_pk_add_f32 v[162:163], v[162:163], 1.0 op_sel_hi:[1,0]
	v_pk_add_f32 v[164:165], v[164:165], 1.0 op_sel_hi:[1,0]
	v_pk_add_f32 v[166:167], v[166:167], 1.0 op_sel_hi:[1,0]
	v_rcp_f32_e32 v160, v160
	v_rcp_f32_e32 v161, v161
	v_rcp_f32_e32 v162, v162
	v_rcp_f32_e32 v163, v163
	v_rcp_f32_e32 v164, v164
	v_rcp_f32_e32 v165, v165
	v_rcp_f32_e32 v166, v166
	v_rcp_f32_e32 v167, v167
	v_pk_mul_f32 v[160:161], v[108:109], v[160:161]
	v_pk_mul_f32 v[162:163], v[110:111], v[162:163]
	v_pk_mul_f32 v[164:165], v[100:101], v[164:165]
	v_pk_mul_f32 v[166:167], v[102:103], v[166:167]
	v_pk_mul_f32 v[160:161], v[104:105], v[160:161]
	v_pk_mul_f32 v[162:163], v[106:107], v[162:163]
	v_pk_mul_f32 v[164:165], v[96:97], v[164:165]
	v_pk_mul_f32 v[166:167], v[98:99], v[166:167]
	v_cvt_pk_bf16_f32 v172, v160, v161
	v_cvt_pk_bf16_f32 v173, v162, v163
	v_cvt_pk_bf16_f32 v174, v164, v165
	v_cvt_pk_bf16_f32 v175, v166, v167
	global_store_dwordx2 v[158:159], v[172:173], off
	global_store_dwordx2 v[158:159], v[174:175], off offset:128
	v_pk_mul_f32 v[92:93], v[92:93], v[248:249] op_sel_hi:[1,0]
	v_pk_mul_f32 v[94:95], v[94:95], v[248:249] op_sel_hi:[1,0]
	v_pk_mul_f32 v[84:85], v[84:85], v[248:249] op_sel_hi:[1,0]
	v_pk_mul_f32 v[86:87], v[86:87], v[248:249] op_sel_hi:[1,0]
	v_pk_mul_f32 v[88:89], v[88:89], v[248:249] op_sel_hi:[1,0]
	v_pk_mul_f32 v[90:91], v[90:91], v[248:249] op_sel_hi:[1,0]
	v_pk_mul_f32 v[80:81], v[80:81], v[248:249] op_sel_hi:[1,0]
	v_pk_mul_f32 v[82:83], v[82:83], v[248:249] op_sel_hi:[1,0]
	v_add_u32_e32 v141, 0x20, v140
	v_pk_mul_f32 v[160:161], v[92:93], v[176:177] op_sel_hi:[1,0]
	v_pk_mul_f32 v[162:163], v[94:95], v[176:177] op_sel_hi:[1,0]
	v_pk_mul_f32 v[164:165], v[84:85], v[176:177] op_sel_hi:[1,0]
	v_pk_mul_f32 v[166:167], v[86:87], v[176:177] op_sel_hi:[1,0]
	v_mad_i64_i32 v[204:205], s[2:3], v141, s78, v[138:139]
	v_exp_f32_e32 v160, v160
	v_exp_f32_e32 v161, v161
	v_exp_f32_e32 v162, v162
	v_exp_f32_e32 v163, v163
	v_exp_f32_e32 v164, v164
	v_exp_f32_e32 v165, v165
	v_exp_f32_e32 v166, v166
	v_exp_f32_e32 v167, v167
	v_pk_add_f32 v[160:161], v[160:161], 1.0 op_sel_hi:[1,0]
	v_pk_add_f32 v[162:163], v[162:163], 1.0 op_sel_hi:[1,0]
	v_pk_add_f32 v[164:165], v[164:165], 1.0 op_sel_hi:[1,0]
	v_pk_add_f32 v[166:167], v[166:167], 1.0 op_sel_hi:[1,0]
	v_rcp_f32_e32 v160, v160
	v_rcp_f32_e32 v161, v161
	v_rcp_f32_e32 v162, v162
	v_rcp_f32_e32 v163, v163
	v_rcp_f32_e32 v164, v164
	v_rcp_f32_e32 v165, v165
	v_rcp_f32_e32 v166, v166
	v_rcp_f32_e32 v167, v167
	v_pk_mul_f32 v[160:161], v[92:93], v[160:161]
	v_pk_mul_f32 v[162:163], v[94:95], v[162:163]
	v_pk_mul_f32 v[164:165], v[84:85], v[164:165]
	v_pk_mul_f32 v[166:167], v[86:87], v[166:167]
	v_pk_mul_f32 v[160:161], v[88:89], v[160:161]
	v_pk_mul_f32 v[162:163], v[90:91], v[162:163]
	v_pk_mul_f32 v[164:165], v[80:81], v[164:165]
	v_pk_mul_f32 v[166:167], v[82:83], v[166:167]
	v_cvt_pk_bf16_f32 v168, v160, v161
	v_cvt_pk_bf16_f32 v169, v162, v163
	v_cvt_pk_bf16_f32 v170, v164, v165
	v_cvt_pk_bf16_f32 v171, v166, v167
	global_store_dwordx2 v[204:205], v[168:169], off
	global_store_dwordx2 v[204:205], v[170:171], off offset:128
	v_pk_mul_f32 v[76:77], v[76:77], v[248:249] op_sel:[0,1] op_sel_hi:[1,1]
	v_pk_mul_f32 v[78:79], v[78:79], v[248:249] op_sel:[0,1] op_sel_hi:[1,1]
	v_pk_mul_f32 v[68:69], v[68:69], v[248:249] op_sel:[0,1] op_sel_hi:[1,1]
	v_pk_mul_f32 v[70:71], v[70:71], v[248:249] op_sel:[0,1] op_sel_hi:[1,1]
	v_pk_mul_f32 v[72:73], v[72:73], v[248:249] op_sel:[0,1] op_sel_hi:[1,1]
	v_pk_mul_f32 v[74:75], v[74:75], v[248:249] op_sel:[0,1] op_sel_hi:[1,1]
	v_pk_mul_f32 v[64:65], v[64:65], v[248:249] op_sel:[0,1] op_sel_hi:[1,1]
	v_pk_mul_f32 v[66:67], v[66:67], v[248:249] op_sel:[0,1] op_sel_hi:[1,1]
	v_add_u32_e32 v141, 0x30, v140
	v_pk_mul_f32 v[160:161], v[76:77], v[176:177] op_sel_hi:[1,0]
	v_pk_mul_f32 v[162:163], v[78:79], v[176:177] op_sel_hi:[1,0]
	v_pk_mul_f32 v[164:165], v[68:69], v[176:177] op_sel_hi:[1,0]
	v_pk_mul_f32 v[166:167], v[70:71], v[176:177] op_sel_hi:[1,0]
	v_mad_i64_i32 v[206:207], s[2:3], v141, s78, v[138:139]
	v_exp_f32_e32 v160, v160
	v_exp_f32_e32 v161, v161
	v_exp_f32_e32 v162, v162
	v_exp_f32_e32 v163, v163
	v_exp_f32_e32 v164, v164
	v_exp_f32_e32 v165, v165
	v_exp_f32_e32 v166, v166
	v_exp_f32_e32 v167, v167
	v_pk_add_f32 v[160:161], v[160:161], 1.0 op_sel_hi:[1,0]
	v_pk_add_f32 v[162:163], v[162:163], 1.0 op_sel_hi:[1,0]
	v_pk_add_f32 v[164:165], v[164:165], 1.0 op_sel_hi:[1,0]
	v_pk_add_f32 v[166:167], v[166:167], 1.0 op_sel_hi:[1,0]
	v_rcp_f32_e32 v160, v160
	v_rcp_f32_e32 v161, v161
	v_rcp_f32_e32 v162, v162
	v_rcp_f32_e32 v163, v163
	v_rcp_f32_e32 v164, v164
	v_rcp_f32_e32 v165, v165
	v_rcp_f32_e32 v166, v166
	v_rcp_f32_e32 v167, v167
	v_pk_mul_f32 v[160:161], v[76:77], v[160:161]
	v_pk_mul_f32 v[162:163], v[78:79], v[162:163]
	v_pk_mul_f32 v[164:165], v[68:69], v[164:165]
	v_pk_mul_f32 v[166:167], v[70:71], v[166:167]
	v_pk_mul_f32 v[160:161], v[72:73], v[160:161]
	v_pk_mul_f32 v[162:163], v[74:75], v[162:163]
	v_pk_mul_f32 v[164:165], v[64:65], v[164:165]
	v_pk_mul_f32 v[166:167], v[66:67], v[166:167]
	v_cvt_pk_bf16_f32 v172, v160, v161
	v_cvt_pk_bf16_f32 v173, v162, v163
	v_cvt_pk_bf16_f32 v174, v164, v165
	v_cvt_pk_bf16_f32 v175, v166, v167
	global_store_dwordx2 v[206:207], v[172:173], off
	global_store_dwordx2 v[206:207], v[174:175], off offset:128
	v_pk_mul_f32 v[60:61], v[60:61], v[250:251] op_sel_hi:[1,0]
	v_pk_mul_f32 v[62:63], v[62:63], v[250:251] op_sel_hi:[1,0]
	v_pk_mul_f32 v[52:53], v[52:53], v[250:251] op_sel_hi:[1,0]
	v_pk_mul_f32 v[54:55], v[54:55], v[250:251] op_sel_hi:[1,0]
	v_pk_mul_f32 v[56:57], v[56:57], v[250:251] op_sel_hi:[1,0]
	v_pk_mul_f32 v[58:59], v[58:59], v[250:251] op_sel_hi:[1,0]
	v_pk_mul_f32 v[48:49], v[48:49], v[250:251] op_sel_hi:[1,0]
	v_pk_mul_f32 v[50:51], v[50:51], v[250:251] op_sel_hi:[1,0]
	v_add_u32_e32 v141, 0x80, v140
	v_pk_mul_f32 v[160:161], v[60:61], v[176:177] op_sel_hi:[1,0]
	v_pk_mul_f32 v[162:163], v[62:63], v[176:177] op_sel_hi:[1,0]
	v_pk_mul_f32 v[164:165], v[52:53], v[176:177] op_sel_hi:[1,0]
	v_pk_mul_f32 v[166:167], v[54:55], v[176:177] op_sel_hi:[1,0]
	v_mad_i64_i32 v[156:157], s[2:3], v141, s78, v[138:139]
	v_exp_f32_e32 v160, v160
	v_exp_f32_e32 v161, v161
	v_exp_f32_e32 v162, v162
	v_exp_f32_e32 v163, v163
	v_exp_f32_e32 v164, v164
	v_exp_f32_e32 v165, v165
	v_exp_f32_e32 v166, v166
	v_exp_f32_e32 v167, v167
	v_pk_add_f32 v[160:161], v[160:161], 1.0 op_sel_hi:[1,0]
	v_pk_add_f32 v[162:163], v[162:163], 1.0 op_sel_hi:[1,0]
	v_pk_add_f32 v[164:165], v[164:165], 1.0 op_sel_hi:[1,0]
	v_pk_add_f32 v[166:167], v[166:167], 1.0 op_sel_hi:[1,0]
	v_rcp_f32_e32 v160, v160
	v_rcp_f32_e32 v161, v161
	v_rcp_f32_e32 v162, v162
	v_rcp_f32_e32 v163, v163
	v_rcp_f32_e32 v164, v164
	v_rcp_f32_e32 v165, v165
	v_rcp_f32_e32 v166, v166
	v_rcp_f32_e32 v167, v167
	v_pk_mul_f32 v[160:161], v[60:61], v[160:161]
	v_pk_mul_f32 v[162:163], v[62:63], v[162:163]
	v_pk_mul_f32 v[164:165], v[52:53], v[164:165]
	v_pk_mul_f32 v[166:167], v[54:55], v[166:167]
	v_pk_mul_f32 v[160:161], v[56:57], v[160:161]
	v_pk_mul_f32 v[162:163], v[58:59], v[162:163]
	v_pk_mul_f32 v[164:165], v[48:49], v[164:165]
	v_pk_mul_f32 v[166:167], v[50:51], v[166:167]
	v_cvt_pk_bf16_f32 v168, v160, v161
	v_cvt_pk_bf16_f32 v169, v162, v163
	v_cvt_pk_bf16_f32 v170, v164, v165
	v_cvt_pk_bf16_f32 v171, v166, v167
	global_store_dwordx2 v[156:157], v[168:169], off
	global_store_dwordx2 v[156:157], v[170:171], off offset:128
	v_pk_mul_f32 v[44:45], v[44:45], v[250:251] op_sel:[0,1] op_sel_hi:[1,1]
	v_pk_mul_f32 v[46:47], v[46:47], v[250:251] op_sel:[0,1] op_sel_hi:[1,1]
	v_pk_mul_f32 v[36:37], v[36:37], v[250:251] op_sel:[0,1] op_sel_hi:[1,1]
	v_pk_mul_f32 v[38:39], v[38:39], v[250:251] op_sel:[0,1] op_sel_hi:[1,1]
	v_pk_mul_f32 v[40:41], v[40:41], v[250:251] op_sel:[0,1] op_sel_hi:[1,1]
	v_pk_mul_f32 v[42:43], v[42:43], v[250:251] op_sel:[0,1] op_sel_hi:[1,1]
	v_pk_mul_f32 v[32:33], v[32:33], v[250:251] op_sel:[0,1] op_sel_hi:[1,1]
	v_pk_mul_f32 v[34:35], v[34:35], v[250:251] op_sel:[0,1] op_sel_hi:[1,1]
	v_add_u32_e32 v141, 0x90, v140
	v_pk_mul_f32 v[160:161], v[44:45], v[176:177] op_sel_hi:[1,0]
	v_pk_mul_f32 v[162:163], v[46:47], v[176:177] op_sel_hi:[1,0]
	v_pk_mul_f32 v[164:165], v[36:37], v[176:177] op_sel_hi:[1,0]
	v_pk_mul_f32 v[166:167], v[38:39], v[176:177] op_sel_hi:[1,0]
	v_mad_i64_i32 v[158:159], s[2:3], v141, s78, v[138:139]
	v_exp_f32_e32 v160, v160
	v_exp_f32_e32 v161, v161
	v_exp_f32_e32 v162, v162
	v_exp_f32_e32 v163, v163
	v_exp_f32_e32 v164, v164
	v_exp_f32_e32 v165, v165
	v_exp_f32_e32 v166, v166
	v_exp_f32_e32 v167, v167
	v_pk_add_f32 v[160:161], v[160:161], 1.0 op_sel_hi:[1,0]
	v_pk_add_f32 v[162:163], v[162:163], 1.0 op_sel_hi:[1,0]
	v_pk_add_f32 v[164:165], v[164:165], 1.0 op_sel_hi:[1,0]
	v_pk_add_f32 v[166:167], v[166:167], 1.0 op_sel_hi:[1,0]
	v_rcp_f32_e32 v160, v160
	v_rcp_f32_e32 v161, v161
	v_rcp_f32_e32 v162, v162
	v_rcp_f32_e32 v163, v163
	v_rcp_f32_e32 v164, v164
	v_rcp_f32_e32 v165, v165
	v_rcp_f32_e32 v166, v166
	v_rcp_f32_e32 v167, v167
	v_pk_mul_f32 v[160:161], v[44:45], v[160:161]
	v_pk_mul_f32 v[162:163], v[46:47], v[162:163]
	v_pk_mul_f32 v[164:165], v[36:37], v[164:165]
	v_pk_mul_f32 v[166:167], v[38:39], v[166:167]
	v_pk_mul_f32 v[160:161], v[40:41], v[160:161]
	v_pk_mul_f32 v[162:163], v[42:43], v[162:163]
	v_pk_mul_f32 v[164:165], v[32:33], v[164:165]
	v_pk_mul_f32 v[166:167], v[34:35], v[166:167]
	v_cvt_pk_bf16_f32 v172, v160, v161
	v_cvt_pk_bf16_f32 v173, v162, v163
	v_cvt_pk_bf16_f32 v174, v164, v165
	v_cvt_pk_bf16_f32 v175, v166, v167
	global_store_dwordx2 v[158:159], v[172:173], off
	global_store_dwordx2 v[158:159], v[174:175], off offset:128
	v_pk_mul_f32 v[28:29], v[28:29], v[252:253] op_sel_hi:[1,0]
	v_pk_mul_f32 v[30:31], v[30:31], v[252:253] op_sel_hi:[1,0]
	v_pk_mul_f32 v[20:21], v[20:21], v[252:253] op_sel_hi:[1,0]
	v_pk_mul_f32 v[22:23], v[22:23], v[252:253] op_sel_hi:[1,0]
	v_pk_mul_f32 v[24:25], v[24:25], v[252:253] op_sel_hi:[1,0]
	v_pk_mul_f32 v[26:27], v[26:27], v[252:253] op_sel_hi:[1,0]
	v_pk_mul_f32 v[16:17], v[16:17], v[252:253] op_sel_hi:[1,0]
	v_pk_mul_f32 v[18:19], v[18:19], v[252:253] op_sel_hi:[1,0]
	v_add_u32_e32 v141, 0xa0, v140
	v_pk_mul_f32 v[160:161], v[28:29], v[176:177] op_sel_hi:[1,0]
	v_pk_mul_f32 v[162:163], v[30:31], v[176:177] op_sel_hi:[1,0]
	v_pk_mul_f32 v[164:165], v[20:21], v[176:177] op_sel_hi:[1,0]
	v_pk_mul_f32 v[166:167], v[22:23], v[176:177] op_sel_hi:[1,0]
	v_mad_i64_i32 v[204:205], s[2:3], v141, s78, v[138:139]
	v_exp_f32_e32 v160, v160
	v_exp_f32_e32 v161, v161
	v_exp_f32_e32 v162, v162
	v_exp_f32_e32 v163, v163
	v_exp_f32_e32 v164, v164
	v_exp_f32_e32 v165, v165
	v_exp_f32_e32 v166, v166
	v_exp_f32_e32 v167, v167
	v_pk_add_f32 v[160:161], v[160:161], 1.0 op_sel_hi:[1,0]
	v_pk_add_f32 v[162:163], v[162:163], 1.0 op_sel_hi:[1,0]
	v_pk_add_f32 v[164:165], v[164:165], 1.0 op_sel_hi:[1,0]
	v_pk_add_f32 v[166:167], v[166:167], 1.0 op_sel_hi:[1,0]
	v_rcp_f32_e32 v160, v160
	v_rcp_f32_e32 v161, v161
	v_rcp_f32_e32 v162, v162
	v_rcp_f32_e32 v163, v163
	v_rcp_f32_e32 v164, v164
	v_rcp_f32_e32 v165, v165
	v_rcp_f32_e32 v166, v166
	v_rcp_f32_e32 v167, v167
	v_pk_mul_f32 v[160:161], v[28:29], v[160:161]
	v_pk_mul_f32 v[162:163], v[30:31], v[162:163]
	v_pk_mul_f32 v[164:165], v[20:21], v[164:165]
	v_pk_mul_f32 v[166:167], v[22:23], v[166:167]
	v_pk_mul_f32 v[160:161], v[24:25], v[160:161]
	v_pk_mul_f32 v[162:163], v[26:27], v[162:163]
	v_pk_mul_f32 v[164:165], v[16:17], v[164:165]
	v_pk_mul_f32 v[166:167], v[18:19], v[166:167]
	v_cvt_pk_bf16_f32 v168, v160, v161
	v_cvt_pk_bf16_f32 v169, v162, v163
	v_cvt_pk_bf16_f32 v170, v164, v165
	v_cvt_pk_bf16_f32 v171, v166, v167
	global_store_dwordx2 v[204:205], v[168:169], off
	global_store_dwordx2 v[204:205], v[170:171], off offset:128
	v_pk_mul_f32 v[12:13], v[12:13], v[252:253] op_sel:[0,1] op_sel_hi:[1,1]
	v_pk_mul_f32 v[14:15], v[14:15], v[252:253] op_sel:[0,1] op_sel_hi:[1,1]
	v_pk_mul_f32 v[4:5], v[4:5], v[252:253] op_sel:[0,1] op_sel_hi:[1,1]
	v_pk_mul_f32 v[6:7], v[6:7], v[252:253] op_sel:[0,1] op_sel_hi:[1,1]
	v_pk_mul_f32 v[8:9], v[8:9], v[252:253] op_sel:[0,1] op_sel_hi:[1,1]
	v_pk_mul_f32 v[10:11], v[10:11], v[252:253] op_sel:[0,1] op_sel_hi:[1,1]
	v_pk_mul_f32 v[0:1], v[0:1], v[252:253] op_sel:[0,1] op_sel_hi:[1,1]
	v_pk_mul_f32 v[2:3], v[2:3], v[252:253] op_sel:[0,1] op_sel_hi:[1,1]
	v_add_u32_e32 v141, 0xb0, v140
	v_pk_mul_f32 v[160:161], v[12:13], v[176:177] op_sel_hi:[1,0]
	v_pk_mul_f32 v[162:163], v[14:15], v[176:177] op_sel_hi:[1,0]
	v_pk_mul_f32 v[164:165], v[4:5], v[176:177] op_sel_hi:[1,0]
	v_pk_mul_f32 v[166:167], v[6:7], v[176:177] op_sel_hi:[1,0]
	v_mad_i64_i32 v[206:207], s[2:3], v141, s78, v[138:139]
	v_exp_f32_e32 v160, v160
	v_exp_f32_e32 v161, v161
	v_exp_f32_e32 v162, v162
	v_exp_f32_e32 v163, v163
	v_exp_f32_e32 v164, v164
	v_exp_f32_e32 v165, v165
	v_exp_f32_e32 v166, v166
	v_exp_f32_e32 v167, v167
	v_pk_add_f32 v[160:161], v[160:161], 1.0 op_sel_hi:[1,0]
	v_pk_add_f32 v[162:163], v[162:163], 1.0 op_sel_hi:[1,0]
	v_pk_add_f32 v[164:165], v[164:165], 1.0 op_sel_hi:[1,0]
	v_pk_add_f32 v[166:167], v[166:167], 1.0 op_sel_hi:[1,0]
	v_rcp_f32_e32 v160, v160
	v_rcp_f32_e32 v161, v161
	v_rcp_f32_e32 v162, v162
	v_rcp_f32_e32 v163, v163
	v_rcp_f32_e32 v164, v164
	v_rcp_f32_e32 v165, v165
	v_rcp_f32_e32 v166, v166
	v_rcp_f32_e32 v167, v167
	v_pk_mul_f32 v[160:161], v[12:13], v[160:161]
	v_pk_mul_f32 v[162:163], v[14:15], v[162:163]
	v_pk_mul_f32 v[164:165], v[4:5], v[164:165]
	v_pk_mul_f32 v[166:167], v[6:7], v[166:167]
	v_pk_mul_f32 v[160:161], v[8:9], v[160:161]
	v_pk_mul_f32 v[162:163], v[10:11], v[162:163]
	v_pk_mul_f32 v[164:165], v[0:1], v[164:165]
	v_pk_mul_f32 v[166:167], v[2:3], v[166:167]
	v_cvt_pk_bf16_f32 v172, v160, v161
	v_cvt_pk_bf16_f32 v173, v162, v163
	v_cvt_pk_bf16_f32 v174, v164, v165
	v_cvt_pk_bf16_f32 v175, v166, v167
	global_store_dwordx2 v[206:207], v[172:173], off
	global_store_dwordx2 v[206:207], v[174:175], off offset:128
	s_waitcnt vmcnt(16)
	v_add_f32_e32 v208, v209, v208
	v_add_f32_e32 v212, v213, v212
	v_add_f32_e32 v216, v217, v216
	v_add_f32_e32 v220, v221, v220
	v_add_f32_e32 v224, v225, v224
	v_add_f32_e32 v228, v229, v228
	v_add_f32_e32 v232, v233, v232
	v_add_f32_e32 v236, v237, v236
	v_add_f32_e32 v210, v210, v211
	v_add_f32_e32 v214, v214, v215
	v_add_f32_e32 v218, v218, v219
	v_add_f32_e32 v222, v222, v223
	v_add_f32_e32 v226, v226, v227
	v_add_f32_e32 v230, v230, v231
	v_add_f32_e32 v234, v234, v235
	v_add_f32_e32 v238, v238, v239
	v_add_f32_e32 v208, v208, v210
	v_add_f32_e32 v212, v212, v214
	v_add_f32_e32 v216, v216, v218
	v_add_f32_e32 v220, v220, v222
	v_add_f32_e32 v224, v224, v226
	v_add_f32_e32 v228, v228, v230
	v_add_f32_e32 v232, v232, v234
	v_add_f32_e32 v236, v236, v238
	v_fmamk_f32 v208, v208, 0x3a800000, v184
	v_fmamk_f32 v212, v212, 0x3a800000, v184
	v_fmamk_f32 v216, v216, 0x3a800000, v184
	v_fmamk_f32 v220, v220, 0x3a800000, v184
	v_fmamk_f32 v224, v224, 0x3a800000, v184
	v_fmamk_f32 v228, v228, 0x3a800000, v184
	v_fmamk_f32 v232, v232, 0x3a800000, v184
	v_fmamk_f32 v236, v236, 0x3a800000, v184
	v_rsq_f32_e32 v202, v208
	v_rsq_f32_e32 v203, v212
	v_rsq_f32_e32 v248, v216
	v_rsq_f32_e32 v249, v220
	v_rsq_f32_e32 v250, v224
	v_rsq_f32_e32 v251, v228
	v_rsq_f32_e32 v252, v232
	v_rsq_f32_e32 v253, v236
	s_mov_b64 s[2:3], -1
	s_andn2_b64 vcc, exec, s[38:39]
	s_cbranch_vccnz .LBB0_307
	s_andn2_b64 vcc, exec, s[40:41]
	s_cbranch_vccnz .LBB0_306
	s_barrier
	s_branch .LBB0_306

.LBB0_1299:
	s_add_u32 s44, s2, 0x1ca40000
	s_addc_u32 s45, s3, 0
	s_lshl_b32 s2, s33, 5
	s_and_b32 s5, s2, 0x60
	s_add_i32 m0, s59, 0x18000
	v_lshl_add_u64 v[6:7], v[6:7], 0, s[26:27]
	s_lshl_b32 s4, s39, 13
	s_lshl_b32 s46, s5, 7
	s_waitcnt vmcnt(2)
	s_barrier
	global_load_lds_dwordx4 v[6:7], off
	v_lshl_add_u64 v[4:5], v[4:5], 0, s[26:27]
	s_add_i32 m0, s59, 0x1a000
	s_add_i32 s67, s59, 0x8000
	s_add_i32 s68, s59, 0xa000
	global_load_lds_dwordx4 v[4:5], off
	v_lshl_add_u64 v[0:1], v[0:1], 0, s[26:27]
	s_mov_b32 m0, s67
	s_add_u32 s2, s60, 0x40080
	global_load_lds_dwordx4 v[0:1], off
	v_lshl_add_u64 v[0:1], v[2:3], 0, s[26:27]
	s_mov_b32 m0, s68
	s_addc_u32 s3, s61, 0
	global_load_lds_dwordx4 v[0:1], off
	s_add_i32 m0, s59, 0x1c000
	v_lshl_add_u64 v[0:1], s[2:3], 0, v[144:145]
	global_load_lds_dwordx4 v[0:1], off
	v_lshl_add_u64 v[0:1], s[2:3], 0, v[128:129]
	s_add_i32 m0, s59, 0x1e000
	s_cmpk_lt_u32 s36, 0x100
	global_load_lds_dwordx4 v[0:1], off
	v_lshrrev_b32_e32 v1, 1, v8
	v_and_b32_e32 v1, 24, v1
	v_and_b32_e32 v0, 15, v8
	v_lshlrev_b32_e32 v2, 1, v1
	v_lshl_or_b32 v142, s39, 6, v0
	v_lshl_or_b32 v0, v0, 6, v2
	v_lshlrev_b32_e32 v2, 2, v8
	v_and_b32_e32 v2, 32, v2
	v_bitop3_b32 v3, v0, s4, v2 bitop3:0xde
	v_bitop3_b32 v143, v0, s46, v2 bitop3:0xde
	v_lshlrev_b32_e32 v0, 14, v13
	v_and_b32_e32 v0, 0xffff8000, v0
	v_or_b32_e32 v154, s5, v1
	v_lshl_add_u32 v0, v12, 11, v0
	v_and_b32_e32 v1, 1, v13
	v_lshl_or_b32 v0, v1, 6, v0
	v_lshl_add_u32 v134, v14, 1, v0
	v_lshlrev_b32_e32 v0, 14, v9
	v_and_b32_e32 v0, 0xffff8000, v0
	s_waitcnt vmcnt(6)
	v_lshl_add_u32 v0, v10, 11, v0
	v_and_b32_e32 v1, 1, v9
	v_lshl_or_b32 v0, v1, 6, v0
	s_sext_i32_i16 s33, s38
	s_cselect_b64 s[46:47], -1, 0
	v_mov_b32_e32 v135, v145
	v_lshl_add_u32 v136, v11, 1, v0
	v_mov_b32_e32 v137, v145
	s_mov_b32 s69, 0
	v_add_u32_e32 v155, 0, v3
	s_barrier
	v_lshl_add_u32 v96, s58, 8, v142
	v_ashrrev_i32_e32 v97, 31, v96
	v_lshl_add_u64 v[96:97], v[96:97], 4, s[44:45]
	global_load_dwordx4 v[64:67], v[96:97], off
	global_load_dwordx4 v[68:71], v[96:97], off offset:256
	global_load_dwordx4 v[72:75], v[96:97], off offset:512
	global_load_dwordx4 v[76:79], v[96:97], off offset:768
	global_load_dwordx4 v[80:83], v[96:97], off offset:2048
	global_load_dwordx4 v[84:87], v[96:97], off offset:2304
	global_load_dwordx4 v[88:91], v[96:97], off offset:2560
	global_load_dwordx4 v[92:95], v[96:97], off offset:2816
	s_waitcnt vmcnt(0)
	v_add_f32_e32 v64, v65, v64
	v_add_f32_e32 v68, v69, v68
	v_add_f32_e32 v72, v73, v72
	v_add_f32_e32 v76, v77, v76
	v_add_f32_e32 v80, v81, v80
	v_add_f32_e32 v84, v85, v84
	v_add_f32_e32 v88, v89, v88
	v_add_f32_e32 v92, v93, v92
	v_add_f32_e32 v66, v66, v67
	v_add_f32_e32 v70, v70, v71
	v_add_f32_e32 v74, v74, v75
	v_add_f32_e32 v78, v78, v79
	v_add_f32_e32 v82, v82, v83
	v_add_f32_e32 v86, v86, v87
	v_add_f32_e32 v90, v90, v91
	v_add_f32_e32 v94, v94, v95
	v_add_f32_e32 v64, v64, v66
	v_add_f32_e32 v68, v68, v70
	v_add_f32_e32 v72, v72, v74
	v_add_f32_e32 v76, v76, v78
	v_add_f32_e32 v80, v80, v82
	v_add_f32_e32 v84, v84, v86
	v_add_f32_e32 v88, v88, v90
	v_add_f32_e32 v92, v92, v94
	v_fmamk_f32 v64, v64, 0x3a800000, v184
	v_fmamk_f32 v68, v68, 0x3a800000, v184
	v_fmamk_f32 v72, v72, 0x3a800000, v184
	v_fmamk_f32 v76, v76, 0x3a800000, v184
	v_fmamk_f32 v80, v80, 0x3a800000, v184
	v_fmamk_f32 v84, v84, 0x3a800000, v184
	v_fmamk_f32 v88, v88, 0x3a800000, v184
	v_fmamk_f32 v92, v92, 0x3a800000, v184
	v_rsq_f32_e32 v246, v64
	v_rsq_f32_e32 v247, v68
	v_rsq_f32_e32 v248, v72
	v_rsq_f32_e32 v249, v76
	v_rsq_f32_e32 v250, v80
	v_rsq_f32_e32 v251, v84
	v_rsq_f32_e32 v252, v88
	v_rsq_f32_e32 v253, v92
	s_branch .LBB0_1302

.LBB0_1305:
	s_add_u32 s4, s2, 0xfffc0080
	s_addc_u32 s5, s3, -1
	s_add_i32 s74, 0, 0x10000
	s_cmp_eq_u32 s73, 12
	s_cselect_b32 s61, s36, s5
	s_cselect_b32 s60, s51, s4
	s_cselect_b32 s35, s49, s72
	s_cselect_b32 s34, s70, s71
	s_add_i32 s75, 0, 0x14000
	v_add_u32_e32 v164, s74, v143
	v_add_u32_e32 v180, s75, v143
	ds_read_b128 v[138:141], v164
	ds_read_b128 v[156:159], v164 offset:1024
	ds_read_b128 v[160:163], v164 offset:2048
	ds_read_b128 v[164:167], v164 offset:3072
	ds_read_b128 v[168:171], v180
	ds_read_b128 v[172:175], v180 offset:1024
	ds_read_b128 v[176:179], v180 offset:2048
	ds_read_b128 v[204:207], v180 offset:3072
	v_lshl_add_u64 v[180:181], s[2:3], 0, v[134:135]
	s_add_i32 m0, s59, 0xc000
	ds_read_b128 v[208:211], v155
	ds_read_b128 v[212:215], v155 offset:1024
	ds_read_b128 v[216:219], v155 offset:2048
	ds_read_b128 v[220:223], v155 offset:3072
	ds_read_b128 v[224:227], v155 offset:4096
	ds_read_b128 v[228:231], v155 offset:5120
	ds_read_b128 v[232:235], v155 offset:6144
	ds_read_b128 v[236:239], v155 offset:7168
	global_load_lds_dwordx4 v[180:181], off
	v_lshl_add_u64 v[180:181], s[2:3], 0, v[136:137]
	s_add_i32 m0, s59, 0xe000
	s_nop 0
	global_load_lds_dwordx4 v[180:181], off
	s_waitcnt vmcnt(8)
	s_waitcnt lgkmcnt(0)
	s_barrier
	s_setprio 1
	s_waitcnt lgkmcnt(0)
	v_mfma_f32_16x16x32_bf16 v[124:127], v[138:141], v[208:211], v[124:127]
	v_mfma_f32_16x16x32_bf16 v[120:123], v[160:163], v[208:211], v[120:123]
	v_mfma_f32_16x16x32_bf16 v[108:111], v[138:141], v[216:219], v[108:111]
	v_mfma_f32_16x16x32_bf16 v[104:107], v[160:163], v[216:219], v[104:107]
	v_mfma_f32_16x16x32_bf16 v[92:95], v[138:141], v[224:227], v[92:95]
	v_mfma_f32_16x16x32_bf16 v[88:91], v[160:163], v[224:227], v[88:91]
	v_mfma_f32_16x16x32_bf16 v[76:79], v[138:141], v[232:235], v[76:79]
	v_mfma_f32_16x16x32_bf16 v[72:75], v[160:163], v[232:235], v[72:75]
	v_mfma_f32_16x16x32_bf16 v[124:127], v[156:159], v[212:215], v[124:127]
	v_mfma_f32_16x16x32_bf16 v[120:123], v[164:167], v[212:215], v[120:123]
	v_mfma_f32_16x16x32_bf16 v[108:111], v[156:159], v[220:223], v[108:111]
	v_mfma_f32_16x16x32_bf16 v[104:107], v[164:167], v[220:223], v[104:107]
	v_mfma_f32_16x16x32_bf16 v[92:95], v[156:159], v[228:231], v[92:95]
	v_mfma_f32_16x16x32_bf16 v[88:91], v[164:167], v[228:231], v[88:91]
	v_mfma_f32_16x16x32_bf16 v[76:79], v[156:159], v[236:239], v[76:79]
	v_mfma_f32_16x16x32_bf16 v[72:75], v[164:167], v[236:239], v[72:75]
	s_setprio 0
	s_setprio 1
	v_mfma_f32_16x16x32_bf16 v[116:119], v[168:171], v[208:211], v[116:119]
	v_mfma_f32_16x16x32_bf16 v[112:115], v[176:179], v[208:211], v[112:115]
	v_mfma_f32_16x16x32_bf16 v[100:103], v[168:171], v[216:219], v[100:103]
	v_mfma_f32_16x16x32_bf16 v[96:99], v[176:179], v[216:219], v[96:99]
	v_mfma_f32_16x16x32_bf16 v[84:87], v[168:171], v[224:227], v[84:87]
	v_mfma_f32_16x16x32_bf16 v[80:83], v[176:179], v[224:227], v[80:83]
	v_mfma_f32_16x16x32_bf16 v[68:71], v[168:171], v[232:235], v[68:71]
	v_mfma_f32_16x16x32_bf16 v[64:67], v[176:179], v[232:235], v[64:67]
	v_mfma_f32_16x16x32_bf16 v[116:119], v[172:175], v[212:215], v[116:119]
	v_mfma_f32_16x16x32_bf16 v[112:115], v[204:207], v[212:215], v[112:115]
	v_mfma_f32_16x16x32_bf16 v[100:103], v[172:175], v[220:223], v[100:103]
	v_mfma_f32_16x16x32_bf16 v[96:99], v[204:207], v[220:223], v[96:99]
	v_mfma_f32_16x16x32_bf16 v[84:87], v[172:175], v[228:231], v[84:87]
	v_mfma_f32_16x16x32_bf16 v[80:83], v[204:207], v[228:231], v[80:83]
	v_mfma_f32_16x16x32_bf16 v[68:71], v[172:175], v[236:239], v[68:71]
	v_mfma_f32_16x16x32_bf16 v[64:67], v[204:207], v[236:239], v[64:67]
	s_setprio 0
	s_barrier
	s_add_i32 s4, s74, s1
	v_lshl_add_u64 v[180:181], s[34:35], 0, v[144:145]
	s_mov_b32 m0, s4
	ds_read_b128 v[208:211], v155 offset:16384
	ds_read_b128 v[212:215], v155 offset:17408
	ds_read_b128 v[216:219], v155 offset:18432
	ds_read_b128 v[220:223], v155 offset:19456
	ds_read_b128 v[224:227], v155 offset:20480
	ds_read_b128 v[228:231], v155 offset:21504
	ds_read_b128 v[232:235], v155 offset:22528
	ds_read_b128 v[236:239], v155 offset:23552
	global_load_lds_dwordx4 v[180:181], off
	s_add_i32 m0, s4, 0x2000
	s_add_u32 s4, s34, 0x40000
	v_lshl_add_u64 v[202:203], s[34:35], 0, v[128:129]
	s_addc_u32 s5, s35, 0
	s_add_i32 s74, s75, s1
	global_load_lds_dwordx4 v[202:203], off
	v_lshl_add_u64 v[240:241], s[4:5], 0, v[144:145]
	s_mov_b32 m0, s74
	v_lshl_add_u64 v[242:243], s[60:61], 0, v[130:131]
	global_load_lds_dwordx4 v[240:241], off
	v_lshl_add_u64 v[240:241], s[4:5], 0, v[128:129]
	s_add_i32 m0, s74, 0x2000
	s_nop 0
	global_load_lds_dwordx4 v[240:241], off
	v_lshl_add_u64 v[240:241], s[60:61], 0, v[132:133]
	s_mov_b32 m0, s59
	s_nop 0
	global_load_lds_dwordx4 v[240:241], off
	s_mov_b32 m0, s64
	s_nop 0
	global_load_lds_dwordx4 v[242:243], off
	s_waitcnt vmcnt(8)
	s_waitcnt lgkmcnt(0)
	s_barrier
	s_setprio 1
	s_waitcnt lgkmcnt(0)
	v_mfma_f32_16x16x32_bf16 v[60:63], v[138:141], v[208:211], v[60:63]
	v_mfma_f32_16x16x32_bf16 v[56:59], v[160:163], v[208:211], v[56:59]
	v_mfma_f32_16x16x32_bf16 v[44:47], v[138:141], v[216:219], v[44:47]
	v_mfma_f32_16x16x32_bf16 v[40:43], v[160:163], v[216:219], v[40:43]
	v_mfma_f32_16x16x32_bf16 v[28:31], v[138:141], v[224:227], v[28:31]
	v_mfma_f32_16x16x32_bf16 v[24:27], v[160:163], v[224:227], v[24:27]
	v_mfma_f32_16x16x32_bf16 v[12:15], v[138:141], v[232:235], v[12:15]
	v_mfma_f32_16x16x32_bf16 v[8:11], v[160:163], v[232:235], v[8:11]
	v_mfma_f32_16x16x32_bf16 v[60:63], v[156:159], v[212:215], v[60:63]
	v_mfma_f32_16x16x32_bf16 v[56:59], v[164:167], v[212:215], v[56:59]
	v_mfma_f32_16x16x32_bf16 v[44:47], v[156:159], v[220:223], v[44:47]
	v_mfma_f32_16x16x32_bf16 v[40:43], v[164:167], v[220:223], v[40:43]
	v_mfma_f32_16x16x32_bf16 v[28:31], v[156:159], v[228:231], v[28:31]
	v_mfma_f32_16x16x32_bf16 v[24:27], v[164:167], v[228:231], v[24:27]
	v_mfma_f32_16x16x32_bf16 v[12:15], v[156:159], v[236:239], v[12:15]
	v_mfma_f32_16x16x32_bf16 v[8:11], v[164:167], v[236:239], v[8:11]
	s_setprio 0
	s_setprio 1
	v_mfma_f32_16x16x32_bf16 v[52:55], v[168:171], v[208:211], v[52:55]
	v_mfma_f32_16x16x32_bf16 v[48:51], v[176:179], v[208:211], v[48:51]
	v_mfma_f32_16x16x32_bf16 v[36:39], v[168:171], v[216:219], v[36:39]
	v_mfma_f32_16x16x32_bf16 v[32:35], v[176:179], v[216:219], v[32:35]
	v_mfma_f32_16x16x32_bf16 v[20:23], v[168:171], v[224:227], v[20:23]
	v_mfma_f32_16x16x32_bf16 v[16:19], v[176:179], v[224:227], v[16:19]
	v_mfma_f32_16x16x32_bf16 v[4:7], v[168:171], v[232:235], v[4:7]
	v_mfma_f32_16x16x32_bf16 v[0:3], v[176:179], v[232:235], v[0:3]
	v_mfma_f32_16x16x32_bf16 v[52:55], v[172:175], v[212:215], v[52:55]
	v_mfma_f32_16x16x32_bf16 v[48:51], v[204:207], v[212:215], v[48:51]
	v_mfma_f32_16x16x32_bf16 v[36:39], v[172:175], v[220:223], v[36:39]
	v_mfma_f32_16x16x32_bf16 v[32:35], v[204:207], v[220:223], v[32:35]
	v_mfma_f32_16x16x32_bf16 v[20:23], v[172:175], v[228:231], v[20:23]
	v_mfma_f32_16x16x32_bf16 v[16:19], v[204:207], v[228:231], v[16:19]
	v_mfma_f32_16x16x32_bf16 v[4:7], v[172:175], v[236:239], v[4:7]
	v_mfma_f32_16x16x32_bf16 v[0:3], v[204:207], v[236:239], v[0:3]
	s_setprio 0
	s_barrier
	s_add_i32 s74, 0, 0x18000
	s_add_i32 s75, 0, 0x1c000
	v_add_u32_e32 v164, s74, v143
	v_add_u32_e32 v204, s75, v143
	ds_read_b128 v[138:141], v164
	ds_read_b128 v[156:159], v164 offset:1024
	ds_read_b128 v[160:163], v164 offset:2048
	ds_read_b128 v[164:167], v164 offset:3072
	ds_read_b128 v[168:171], v204
	ds_read_b128 v[172:175], v204 offset:1024
	ds_read_b128 v[176:179], v204 offset:2048
	ds_read_b128 v[204:207], v204 offset:3072
	s_add_u32 s4, s60, 0x40000
	s_addc_u32 s5, s61, 0
	s_mov_b32 m0, s65
	v_lshl_add_u64 v[244:245], s[4:5], 0, v[132:133]
	ds_read_b128 v[208:211], v155 offset:32768
	ds_read_b128 v[212:215], v155 offset:33792
	ds_read_b128 v[216:219], v155 offset:34816
	ds_read_b128 v[220:223], v155 offset:35840
	ds_read_b128 v[224:227], v155 offset:36864
	ds_read_b128 v[228:231], v155 offset:37888
	ds_read_b128 v[232:235], v155 offset:38912
	ds_read_b128 v[236:239], v155 offset:39936
	global_load_lds_dwordx4 v[244:245], off
	v_lshl_add_u64 v[244:245], s[4:5], 0, v[130:131]
	s_mov_b32 m0, s66
	s_nop 0
	global_load_lds_dwordx4 v[244:245], off
	s_waitcnt vmcnt(8)
	s_waitcnt lgkmcnt(0)
	s_barrier
	s_setprio 1
	s_waitcnt lgkmcnt(0)
	v_mfma_f32_16x16x32_bf16 v[124:127], v[138:141], v[208:211], v[124:127]
	v_mfma_f32_16x16x32_bf16 v[120:123], v[160:163], v[208:211], v[120:123]
	v_mfma_f32_16x16x32_bf16 v[108:111], v[138:141], v[216:219], v[108:111]
	v_mfma_f32_16x16x32_bf16 v[104:107], v[160:163], v[216:219], v[104:107]
	v_mfma_f32_16x16x32_bf16 v[92:95], v[138:141], v[224:227], v[92:95]
	v_mfma_f32_16x16x32_bf16 v[88:91], v[160:163], v[224:227], v[88:91]
	v_mfma_f32_16x16x32_bf16 v[76:79], v[138:141], v[232:235], v[76:79]
	v_mfma_f32_16x16x32_bf16 v[72:75], v[160:163], v[232:235], v[72:75]
	v_mfma_f32_16x16x32_bf16 v[124:127], v[156:159], v[212:215], v[124:127]
	v_mfma_f32_16x16x32_bf16 v[120:123], v[164:167], v[212:215], v[120:123]
	v_mfma_f32_16x16x32_bf16 v[108:111], v[156:159], v[220:223], v[108:111]
	v_mfma_f32_16x16x32_bf16 v[104:107], v[164:167], v[220:223], v[104:107]
	v_mfma_f32_16x16x32_bf16 v[92:95], v[156:159], v[228:231], v[92:95]
	v_mfma_f32_16x16x32_bf16 v[88:91], v[164:167], v[228:231], v[88:91]
	v_mfma_f32_16x16x32_bf16 v[76:79], v[156:159], v[236:239], v[76:79]
	v_mfma_f32_16x16x32_bf16 v[72:75], v[164:167], v[236:239], v[72:75]
	s_setprio 0
	s_setprio 1
	v_mfma_f32_16x16x32_bf16 v[116:119], v[168:171], v[208:211], v[116:119]
	v_mfma_f32_16x16x32_bf16 v[112:115], v[176:179], v[208:211], v[112:115]
	v_mfma_f32_16x16x32_bf16 v[100:103], v[168:171], v[216:219], v[100:103]
	v_mfma_f32_16x16x32_bf16 v[96:99], v[176:179], v[216:219], v[96:99]
	v_mfma_f32_16x16x32_bf16 v[84:87], v[168:171], v[224:227], v[84:87]
	v_mfma_f32_16x16x32_bf16 v[80:83], v[176:179], v[224:227], v[80:83]
	v_mfma_f32_16x16x32_bf16 v[68:71], v[168:171], v[232:235], v[68:71]
	v_mfma_f32_16x16x32_bf16 v[64:67], v[176:179], v[232:235], v[64:67]
	v_mfma_f32_16x16x32_bf16 v[116:119], v[172:175], v[212:215], v[116:119]
	v_mfma_f32_16x16x32_bf16 v[112:115], v[204:207], v[212:215], v[112:115]
	v_mfma_f32_16x16x32_bf16 v[100:103], v[172:175], v[220:223], v[100:103]
	v_mfma_f32_16x16x32_bf16 v[96:99], v[204:207], v[220:223], v[96:99]
	v_mfma_f32_16x16x32_bf16 v[84:87], v[172:175], v[228:231], v[84:87]
	v_mfma_f32_16x16x32_bf16 v[80:83], v[204:207], v[228:231], v[80:83]
	v_mfma_f32_16x16x32_bf16 v[68:71], v[172:175], v[236:239], v[68:71]
	v_mfma_f32_16x16x32_bf16 v[64:67], v[204:207], v[236:239], v[64:67]
	s_setprio 0
	s_barrier
	s_add_i32 s4, s74, s1
	v_lshl_add_u64 v[180:181], v[180:181], 0, s[26:27]
	s_mov_b32 m0, s4
	ds_read_b128 v[208:211], v155 offset:49152
	ds_read_b128 v[212:215], v155 offset:50176
	ds_read_b128 v[216:219], v155 offset:51200
	ds_read_b128 v[220:223], v155 offset:52224
	ds_read_b128 v[224:227], v155 offset:53248
	ds_read_b128 v[228:231], v155 offset:54272
	ds_read_b128 v[232:235], v155 offset:55296
	ds_read_b128 v[236:239], v155 offset:56320
	global_load_lds_dwordx4 v[180:181], off
	s_add_i32 m0, s4, 0x2000
	s_add_u32 s4, s34, 0x40080
	v_lshl_add_u64 v[180:181], v[202:203], 0, s[26:27]
	s_addc_u32 s5, s35, 0
	s_add_i32 s34, s75, s1
	global_load_lds_dwordx4 v[180:181], off
	v_lshl_add_u64 v[180:181], s[4:5], 0, v[144:145]
	s_mov_b32 m0, s34
	s_nop 0
	global_load_lds_dwordx4 v[180:181], off
	v_lshl_add_u64 v[180:181], s[4:5], 0, v[128:129]
	s_add_i32 m0, s34, 0x2000
	s_nop 0
	global_load_lds_dwordx4 v[180:181], off
	v_lshl_add_u64 v[180:181], v[240:241], 0, s[26:27]
	s_mov_b32 m0, s67
	s_nop 0
	global_load_lds_dwordx4 v[180:181], off
	v_lshl_add_u64 v[180:181], v[242:243], 0, s[26:27]
	s_mov_b32 m0, s68
	s_nop 0
	global_load_lds_dwordx4 v[180:181], off
	s_waitcnt vmcnt(8)
	s_waitcnt lgkmcnt(0)
	s_barrier
	s_setprio 1
	s_waitcnt lgkmcnt(0)
	v_mfma_f32_16x16x32_bf16 v[60:63], v[138:141], v[208:211], v[60:63]
	v_mfma_f32_16x16x32_bf16 v[56:59], v[160:163], v[208:211], v[56:59]
	v_mfma_f32_16x16x32_bf16 v[44:47], v[138:141], v[216:219], v[44:47]
	v_mfma_f32_16x16x32_bf16 v[40:43], v[160:163], v[216:219], v[40:43]
	v_mfma_f32_16x16x32_bf16 v[28:31], v[138:141], v[224:227], v[28:31]
	v_mfma_f32_16x16x32_bf16 v[24:27], v[160:163], v[224:227], v[24:27]
	v_mfma_f32_16x16x32_bf16 v[12:15], v[138:141], v[232:235], v[12:15]
	v_mfma_f32_16x16x32_bf16 v[8:11], v[160:163], v[232:235], v[8:11]
	v_mfma_f32_16x16x32_bf16 v[60:63], v[156:159], v[212:215], v[60:63]
	v_mfma_f32_16x16x32_bf16 v[56:59], v[164:167], v[212:215], v[56:59]
	v_mfma_f32_16x16x32_bf16 v[44:47], v[156:159], v[220:223], v[44:47]
	v_mfma_f32_16x16x32_bf16 v[40:43], v[164:167], v[220:223], v[40:43]
	v_mfma_f32_16x16x32_bf16 v[28:31], v[156:159], v[228:231], v[28:31]
	v_mfma_f32_16x16x32_bf16 v[24:27], v[164:167], v[228:231], v[24:27]
	v_mfma_f32_16x16x32_bf16 v[12:15], v[156:159], v[236:239], v[12:15]
	v_mfma_f32_16x16x32_bf16 v[8:11], v[164:167], v[236:239], v[8:11]
	s_setprio 0
	s_setprio 1
	v_mfma_f32_16x16x32_bf16 v[52:55], v[168:171], v[208:211], v[52:55]
	v_mfma_f32_16x16x32_bf16 v[48:51], v[176:179], v[208:211], v[48:51]
	v_mfma_f32_16x16x32_bf16 v[36:39], v[168:171], v[216:219], v[36:39]
	v_mfma_f32_16x16x32_bf16 v[32:35], v[176:179], v[216:219], v[32:35]
	v_mfma_f32_16x16x32_bf16 v[20:23], v[168:171], v[224:227], v[20:23]
	v_mfma_f32_16x16x32_bf16 v[16:19], v[176:179], v[224:227], v[16:19]
	v_mfma_f32_16x16x32_bf16 v[4:7], v[168:171], v[232:235], v[4:7]
	v_mfma_f32_16x16x32_bf16 v[0:3], v[176:179], v[232:235], v[0:3]
	v_mfma_f32_16x16x32_bf16 v[52:55], v[172:175], v[212:215], v[52:55]
	v_mfma_f32_16x16x32_bf16 v[48:51], v[204:207], v[212:215], v[48:51]
	v_mfma_f32_16x16x32_bf16 v[36:39], v[172:175], v[220:223], v[36:39]
	v_mfma_f32_16x16x32_bf16 v[32:35], v[204:207], v[220:223], v[32:35]
	v_mfma_f32_16x16x32_bf16 v[20:23], v[172:175], v[228:231], v[20:23]
	v_mfma_f32_16x16x32_bf16 v[16:19], v[204:207], v[228:231], v[16:19]
	v_mfma_f32_16x16x32_bf16 v[4:7], v[172:175], v[236:239], v[4:7]
	v_mfma_f32_16x16x32_bf16 v[0:3], v[204:207], v[236:239], v[0:3]
	s_setprio 0
	s_barrier
	s_add_i32 s73, s73, 2
	s_add_u32 s2, s2, 0x100
	s_addc_u32 s3, s3, 0
	s_add_u32 s71, s71, 0x100
	s_addc_u32 s72, s72, 0
	s_cmp_gt_u32 s73, 13
	s_cbranch_scc0 .LBB0_1305
	s_and_b64 vcc, s[38:39], exec
	s_cselect_b32 s4, s50, s58
	v_lshl_add_u32 v178, s4, 8, v142
	v_ashrrev_i32_e32 v179, 31, v178
	v_lshl_add_u64 v[178:179], v[178:179], 4, s[44:45]
	global_load_dwordx4 v[208:211], v[178:179], off
	global_load_dwordx4 v[212:215], v[178:179], off offset:256
	global_load_dwordx4 v[216:219], v[178:179], off offset:512
	global_load_dwordx4 v[220:223], v[178:179], off offset:768
	global_load_dwordx4 v[224:227], v[178:179], off offset:2048
	global_load_dwordx4 v[228:231], v[178:179], off offset:2304
	global_load_dwordx4 v[232:235], v[178:179], off offset:2560
	global_load_dwordx4 v[236:239], v[178:179], off offset:2816
	s_and_b64 vcc, exec, s[46:47]
	s_cbranch_vccz .LBB0_1308
	s_barrier
.LBB0_1308:
	v_lshl_add_u32 v140, s58, 8, v142
	v_lshl_or_b32 v164, s33, 8, v154
	v_mov_b32_e32 v176, 0xbfb8aa3b
	v_ashrrev_i32_e32 v164, 1, v164
	v_ashrrev_i32_e32 v165, 31, v164
	v_mov_b32_e32 v177, 0xbfb8aa3b
	v_lshl_add_u64 v[138:139], v[164:165], 1, s[42:43]
	v_pk_mul_f32 v[124:125], v[124:125], v[246:247] op_sel_hi:[1,0]
	v_pk_mul_f32 v[126:127], v[126:127], v[246:247] op_sel_hi:[1,0]
	v_pk_mul_f32 v[116:117], v[116:117], v[246:247] op_sel_hi:[1,0]
	v_pk_mul_f32 v[118:119], v[118:119], v[246:247] op_sel_hi:[1,0]
	v_pk_mul_f32 v[120:121], v[120:121], v[246:247] op_sel_hi:[1,0]
	v_pk_mul_f32 v[122:123], v[122:123], v[246:247] op_sel_hi:[1,0]
	v_pk_mul_f32 v[112:113], v[112:113], v[246:247] op_sel_hi:[1,0]
	v_pk_mul_f32 v[114:115], v[114:115], v[246:247] op_sel_hi:[1,0]
	v_pk_mul_f32 v[160:161], v[124:125], v[176:177] op_sel_hi:[1,0]
	v_pk_mul_f32 v[162:163], v[126:127], v[176:177] op_sel_hi:[1,0]
	v_pk_mul_f32 v[164:165], v[116:117], v[176:177] op_sel_hi:[1,0]
	v_pk_mul_f32 v[166:167], v[118:119], v[176:177] op_sel_hi:[1,0]
	v_mad_i64_i32 v[156:157], s[2:3], v140, s78, v[138:139]
	v_exp_f32_e32 v160, v160
	v_exp_f32_e32 v161, v161
	v_exp_f32_e32 v162, v162
	v_exp_f32_e32 v163, v163
	v_exp_f32_e32 v164, v164
	v_exp_f32_e32 v165, v165
	v_exp_f32_e32 v166, v166
	v_exp_f32_e32 v167, v167
	v_pk_add_f32 v[160:161], v[160:161], 1.0 op_sel_hi:[1,0]
	v_pk_add_f32 v[162:163], v[162:163], 1.0 op_sel_hi:[1,0]
	v_pk_add_f32 v[164:165], v[164:165], 1.0 op_sel_hi:[1,0]
	v_pk_add_f32 v[166:167], v[166:167], 1.0 op_sel_hi:[1,0]
	v_rcp_f32_e32 v160, v160
	v_rcp_f32_e32 v161, v161
	v_rcp_f32_e32 v162, v162
	v_rcp_f32_e32 v163, v163
	v_rcp_f32_e32 v164, v164
	v_rcp_f32_e32 v165, v165
	v_rcp_f32_e32 v166, v166
	v_rcp_f32_e32 v167, v167
	v_pk_mul_f32 v[160:161], v[124:125], v[160:161]
	v_pk_mul_f32 v[162:163], v[126:127], v[162:163]
	v_pk_mul_f32 v[164:165], v[116:117], v[164:165]
	v_pk_mul_f32 v[166:167], v[118:119], v[166:167]
	v_pk_mul_f32 v[160:161], v[120:121], v[160:161]
	v_pk_mul_f32 v[162:163], v[122:123], v[162:163]
	v_pk_mul_f32 v[164:165], v[112:113], v[164:165]
	v_pk_mul_f32 v[166:167], v[114:115], v[166:167]
	v_cvt_pk_bf16_f32 v168, v160, v161
	v_cvt_pk_bf16_f32 v169, v162, v163
	v_cvt_pk_bf16_f32 v170, v164, v165
	v_cvt_pk_bf16_f32 v171, v166, v167
	global_store_dwordx2 v[156:157], v[168:169], off
	global_store_dwordx2 v[156:157], v[170:171], off offset:128
	v_pk_mul_f32 v[108:109], v[108:109], v[246:247] op_sel:[0,1] op_sel_hi:[1,1]
	v_pk_mul_f32 v[110:111], v[110:111], v[246:247] op_sel:[0,1] op_sel_hi:[1,1]
	v_pk_mul_f32 v[100:101], v[100:101], v[246:247] op_sel:[0,1] op_sel_hi:[1,1]
	v_pk_mul_f32 v[102:103], v[102:103], v[246:247] op_sel:[0,1] op_sel_hi:[1,1]
	v_pk_mul_f32 v[104:105], v[104:105], v[246:247] op_sel:[0,1] op_sel_hi:[1,1]
	v_pk_mul_f32 v[106:107], v[106:107], v[246:247] op_sel:[0,1] op_sel_hi:[1,1]
	v_pk_mul_f32 v[96:97], v[96:97], v[246:247] op_sel:[0,1] op_sel_hi:[1,1]
	v_pk_mul_f32 v[98:99], v[98:99], v[246:247] op_sel:[0,1] op_sel_hi:[1,1]
	v_add_u32_e32 v141, 0x10, v140
	v_pk_mul_f32 v[160:161], v[108:109], v[176:177] op_sel_hi:[1,0]
	v_pk_mul_f32 v[162:163], v[110:111], v[176:177] op_sel_hi:[1,0]
	v_pk_mul_f32 v[164:165], v[100:101], v[176:177] op_sel_hi:[1,0]
	v_pk_mul_f32 v[166:167], v[102:103], v[176:177] op_sel_hi:[1,0]
	v_mad_i64_i32 v[158:159], s[2:3], v141, s78, v[138:139]
	v_exp_f32_e32 v160, v160
	v_exp_f32_e32 v161, v161
	v_exp_f32_e32 v162, v162
	v_exp_f32_e32 v163, v163
	v_exp_f32_e32 v164, v164
	v_exp_f32_e32 v165, v165
	v_exp_f32_e32 v166, v166
	v_exp_f32_e32 v167, v167
	v_pk_add_f32 v[160:161], v[160:161], 1.0 op_sel_hi:[1,0]
	v_pk_add_f32 v[162:163], v[162:163], 1.0 op_sel_hi:[1,0]
	v_pk_add_f32 v[164:165], v[164:165], 1.0 op_sel_hi:[1,0]
	v_pk_add_f32 v[166:167], v[166:167], 1.0 op_sel_hi:[1,0]
	v_rcp_f32_e32 v160, v160
	v_rcp_f32_e32 v161, v161
	v_rcp_f32_e32 v162, v162
	v_rcp_f32_e32 v163, v163
	v_rcp_f32_e32 v164, v164
	v_rcp_f32_e32 v165, v165
	v_rcp_f32_e32 v166, v166
	v_rcp_f32_e32 v167, v167
	v_pk_mul_f32 v[160:161], v[108:109], v[160:161]
	v_pk_mul_f32 v[162:163], v[110:111], v[162:163]
	v_pk_mul_f32 v[164:165], v[100:101], v[164:165]
	v_pk_mul_f32 v[166:167], v[102:103], v[166:167]
	v_pk_mul_f32 v[160:161], v[104:105], v[160:161]
	v_pk_mul_f32 v[162:163], v[106:107], v[162:163]
	v_pk_mul_f32 v[164:165], v[96:97], v[164:165]
	v_pk_mul_f32 v[166:167], v[98:99], v[166:167]
	v_cvt_pk_bf16_f32 v172, v160, v161
	v_cvt_pk_bf16_f32 v173, v162, v163
	v_cvt_pk_bf16_f32 v174, v164, v165
	v_cvt_pk_bf16_f32 v175, v166, v167
	global_store_dwordx2 v[158:159], v[172:173], off
	global_store_dwordx2 v[158:159], v[174:175], off offset:128
	v_pk_mul_f32 v[92:93], v[92:93], v[248:249] op_sel_hi:[1,0]
	v_pk_mul_f32 v[94:95], v[94:95], v[248:249] op_sel_hi:[1,0]
	v_pk_mul_f32 v[84:85], v[84:85], v[248:249] op_sel_hi:[1,0]
	v_pk_mul_f32 v[86:87], v[86:87], v[248:249] op_sel_hi:[1,0]
	v_pk_mul_f32 v[88:89], v[88:89], v[248:249] op_sel_hi:[1,0]
	v_pk_mul_f32 v[90:91], v[90:91], v[248:249] op_sel_hi:[1,0]
	v_pk_mul_f32 v[80:81], v[80:81], v[248:249] op_sel_hi:[1,0]
	v_pk_mul_f32 v[82:83], v[82:83], v[248:249] op_sel_hi:[1,0]
	v_add_u32_e32 v141, 0x20, v140
	v_pk_mul_f32 v[160:161], v[92:93], v[176:177] op_sel_hi:[1,0]
	v_pk_mul_f32 v[162:163], v[94:95], v[176:177] op_sel_hi:[1,0]
	v_pk_mul_f32 v[164:165], v[84:85], v[176:177] op_sel_hi:[1,0]
	v_pk_mul_f32 v[166:167], v[86:87], v[176:177] op_sel_hi:[1,0]
	v_mad_i64_i32 v[204:205], s[2:3], v141, s78, v[138:139]
	v_exp_f32_e32 v160, v160
	v_exp_f32_e32 v161, v161
	v_exp_f32_e32 v162, v162
	v_exp_f32_e32 v163, v163
	v_exp_f32_e32 v164, v164
	v_exp_f32_e32 v165, v165
	v_exp_f32_e32 v166, v166
	v_exp_f32_e32 v167, v167
	v_pk_add_f32 v[160:161], v[160:161], 1.0 op_sel_hi:[1,0]
	v_pk_add_f32 v[162:163], v[162:163], 1.0 op_sel_hi:[1,0]
	v_pk_add_f32 v[164:165], v[164:165], 1.0 op_sel_hi:[1,0]
	v_pk_add_f32 v[166:167], v[166:167], 1.0 op_sel_hi:[1,0]
	v_rcp_f32_e32 v160, v160
	v_rcp_f32_e32 v161, v161
	v_rcp_f32_e32 v162, v162
	v_rcp_f32_e32 v163, v163
	v_rcp_f32_e32 v164, v164
	v_rcp_f32_e32 v165, v165
	v_rcp_f32_e32 v166, v166
	v_rcp_f32_e32 v167, v167
	v_pk_mul_f32 v[160:161], v[92:93], v[160:161]
	v_pk_mul_f32 v[162:163], v[94:95], v[162:163]
	v_pk_mul_f32 v[164:165], v[84:85], v[164:165]
	v_pk_mul_f32 v[166:167], v[86:87], v[166:167]
	v_pk_mul_f32 v[160:161], v[88:89], v[160:161]
	v_pk_mul_f32 v[162:163], v[90:91], v[162:163]
	v_pk_mul_f32 v[164:165], v[80:81], v[164:165]
	v_pk_mul_f32 v[166:167], v[82:83], v[166:167]
	v_cvt_pk_bf16_f32 v168, v160, v161
	v_cvt_pk_bf16_f32 v169, v162, v163
	v_cvt_pk_bf16_f32 v170, v164, v165
	v_cvt_pk_bf16_f32 v171, v166, v167
	global_store_dwordx2 v[204:205], v[168:169], off
	global_store_dwordx2 v[204:205], v[170:171], off offset:128
	v_pk_mul_f32 v[76:77], v[76:77], v[248:249] op_sel:[0,1] op_sel_hi:[1,1]
	v_pk_mul_f32 v[78:79], v[78:79], v[248:249] op_sel:[0,1] op_sel_hi:[1,1]
	v_pk_mul_f32 v[68:69], v[68:69], v[248:249] op_sel:[0,1] op_sel_hi:[1,1]
	v_pk_mul_f32 v[70:71], v[70:71], v[248:249] op_sel:[0,1] op_sel_hi:[1,1]
	v_pk_mul_f32 v[72:73], v[72:73], v[248:249] op_sel:[0,1] op_sel_hi:[1,1]
	v_pk_mul_f32 v[74:75], v[74:75], v[248:249] op_sel:[0,1] op_sel_hi:[1,1]
	v_pk_mul_f32 v[64:65], v[64:65], v[248:249] op_sel:[0,1] op_sel_hi:[1,1]
	v_pk_mul_f32 v[66:67], v[66:67], v[248:249] op_sel:[0,1] op_sel_hi:[1,1]
	v_add_u32_e32 v141, 0x30, v140
	v_pk_mul_f32 v[160:161], v[76:77], v[176:177] op_sel_hi:[1,0]
	v_pk_mul_f32 v[162:163], v[78:79], v[176:177] op_sel_hi:[1,0]
	v_pk_mul_f32 v[164:165], v[68:69], v[176:177] op_sel_hi:[1,0]
	v_pk_mul_f32 v[166:167], v[70:71], v[176:177] op_sel_hi:[1,0]
	v_mad_i64_i32 v[206:207], s[2:3], v141, s78, v[138:139]
	v_exp_f32_e32 v160, v160
	v_exp_f32_e32 v161, v161
	v_exp_f32_e32 v162, v162
	v_exp_f32_e32 v163, v163
	v_exp_f32_e32 v164, v164
	v_exp_f32_e32 v165, v165
	v_exp_f32_e32 v166, v166
	v_exp_f32_e32 v167, v167
	v_pk_add_f32 v[160:161], v[160:161], 1.0 op_sel_hi:[1,0]
	v_pk_add_f32 v[162:163], v[162:163], 1.0 op_sel_hi:[1,0]
	v_pk_add_f32 v[164:165], v[164:165], 1.0 op_sel_hi:[1,0]
	v_pk_add_f32 v[166:167], v[166:167], 1.0 op_sel_hi:[1,0]
	v_rcp_f32_e32 v160, v160
	v_rcp_f32_e32 v161, v161
	v_rcp_f32_e32 v162, v162
	v_rcp_f32_e32 v163, v163
	v_rcp_f32_e32 v164, v164
	v_rcp_f32_e32 v165, v165
	v_rcp_f32_e32 v166, v166
	v_rcp_f32_e32 v167, v167
	v_pk_mul_f32 v[160:161], v[76:77], v[160:161]
	v_pk_mul_f32 v[162:163], v[78:79], v[162:163]
	v_pk_mul_f32 v[164:165], v[68:69], v[164:165]
	v_pk_mul_f32 v[166:167], v[70:71], v[166:167]
	v_pk_mul_f32 v[160:161], v[72:73], v[160:161]
	v_pk_mul_f32 v[162:163], v[74:75], v[162:163]
	v_pk_mul_f32 v[164:165], v[64:65], v[164:165]
	v_pk_mul_f32 v[166:167], v[66:67], v[166:167]
	v_cvt_pk_bf16_f32 v172, v160, v161
	v_cvt_pk_bf16_f32 v173, v162, v163
	v_cvt_pk_bf16_f32 v174, v164, v165
	v_cvt_pk_bf16_f32 v175, v166, v167
	global_store_dwordx2 v[206:207], v[172:173], off
	global_store_dwordx2 v[206:207], v[174:175], off offset:128
	v_pk_mul_f32 v[60:61], v[60:61], v[250:251] op_sel_hi:[1,0]
	v_pk_mul_f32 v[62:63], v[62:63], v[250:251] op_sel_hi:[1,0]
	v_pk_mul_f32 v[52:53], v[52:53], v[250:251] op_sel_hi:[1,0]
	v_pk_mul_f32 v[54:55], v[54:55], v[250:251] op_sel_hi:[1,0]
	v_pk_mul_f32 v[56:57], v[56:57], v[250:251] op_sel_hi:[1,0]
	v_pk_mul_f32 v[58:59], v[58:59], v[250:251] op_sel_hi:[1,0]
	v_pk_mul_f32 v[48:49], v[48:49], v[250:251] op_sel_hi:[1,0]
	v_pk_mul_f32 v[50:51], v[50:51], v[250:251] op_sel_hi:[1,0]
	v_add_u32_e32 v141, 0x80, v140
	v_pk_mul_f32 v[160:161], v[60:61], v[176:177] op_sel_hi:[1,0]
	v_pk_mul_f32 v[162:163], v[62:63], v[176:177] op_sel_hi:[1,0]
	v_pk_mul_f32 v[164:165], v[52:53], v[176:177] op_sel_hi:[1,0]
	v_pk_mul_f32 v[166:167], v[54:55], v[176:177] op_sel_hi:[1,0]
	v_mad_i64_i32 v[156:157], s[2:3], v141, s78, v[138:139]
	v_exp_f32_e32 v160, v160
	v_exp_f32_e32 v161, v161
	v_exp_f32_e32 v162, v162
	v_exp_f32_e32 v163, v163
	v_exp_f32_e32 v164, v164
	v_exp_f32_e32 v165, v165
	v_exp_f32_e32 v166, v166
	v_exp_f32_e32 v167, v167
	v_pk_add_f32 v[160:161], v[160:161], 1.0 op_sel_hi:[1,0]
	v_pk_add_f32 v[162:163], v[162:163], 1.0 op_sel_hi:[1,0]
	v_pk_add_f32 v[164:165], v[164:165], 1.0 op_sel_hi:[1,0]
	v_pk_add_f32 v[166:167], v[166:167], 1.0 op_sel_hi:[1,0]
	v_rcp_f32_e32 v160, v160
	v_rcp_f32_e32 v161, v161
	v_rcp_f32_e32 v162, v162
	v_rcp_f32_e32 v163, v163
	v_rcp_f32_e32 v164, v164
	v_rcp_f32_e32 v165, v165
	v_rcp_f32_e32 v166, v166
	v_rcp_f32_e32 v167, v167
	v_pk_mul_f32 v[160:161], v[60:61], v[160:161]
	v_pk_mul_f32 v[162:163], v[62:63], v[162:163]
	v_pk_mul_f32 v[164:165], v[52:53], v[164:165]
	v_pk_mul_f32 v[166:167], v[54:55], v[166:167]
	v_pk_mul_f32 v[160:161], v[56:57], v[160:161]
	v_pk_mul_f32 v[162:163], v[58:59], v[162:163]
	v_pk_mul_f32 v[164:165], v[48:49], v[164:165]
	v_pk_mul_f32 v[166:167], v[50:51], v[166:167]
	v_cvt_pk_bf16_f32 v168, v160, v161
	v_cvt_pk_bf16_f32 v169, v162, v163
	v_cvt_pk_bf16_f32 v170, v164, v165
	v_cvt_pk_bf16_f32 v171, v166, v167
	global_store_dwordx2 v[156:157], v[168:169], off
	global_store_dwordx2 v[156:157], v[170:171], off offset:128
	v_pk_mul_f32 v[44:45], v[44:45], v[250:251] op_sel:[0,1] op_sel_hi:[1,1]
	v_pk_mul_f32 v[46:47], v[46:47], v[250:251] op_sel:[0,1] op_sel_hi:[1,1]
	v_pk_mul_f32 v[36:37], v[36:37], v[250:251] op_sel:[0,1] op_sel_hi:[1,1]
	v_pk_mul_f32 v[38:39], v[38:39], v[250:251] op_sel:[0,1] op_sel_hi:[1,1]
	v_pk_mul_f32 v[40:41], v[40:41], v[250:251] op_sel:[0,1] op_sel_hi:[1,1]
	v_pk_mul_f32 v[42:43], v[42:43], v[250:251] op_sel:[0,1] op_sel_hi:[1,1]
	v_pk_mul_f32 v[32:33], v[32:33], v[250:251] op_sel:[0,1] op_sel_hi:[1,1]
	v_pk_mul_f32 v[34:35], v[34:35], v[250:251] op_sel:[0,1] op_sel_hi:[1,1]
	v_add_u32_e32 v141, 0x90, v140
	v_pk_mul_f32 v[160:161], v[44:45], v[176:177] op_sel_hi:[1,0]
	v_pk_mul_f32 v[162:163], v[46:47], v[176:177] op_sel_hi:[1,0]
	v_pk_mul_f32 v[164:165], v[36:37], v[176:177] op_sel_hi:[1,0]
	v_pk_mul_f32 v[166:167], v[38:39], v[176:177] op_sel_hi:[1,0]
	v_mad_i64_i32 v[158:159], s[2:3], v141, s78, v[138:139]
	v_exp_f32_e32 v160, v160
	v_exp_f32_e32 v161, v161
	v_exp_f32_e32 v162, v162
	v_exp_f32_e32 v163, v163
	v_exp_f32_e32 v164, v164
	v_exp_f32_e32 v165, v165
	v_exp_f32_e32 v166, v166
	v_exp_f32_e32 v167, v167
	v_pk_add_f32 v[160:161], v[160:161], 1.0 op_sel_hi:[1,0]
	v_pk_add_f32 v[162:163], v[162:163], 1.0 op_sel_hi:[1,0]
	v_pk_add_f32 v[164:165], v[164:165], 1.0 op_sel_hi:[1,0]
	v_pk_add_f32 v[166:167], v[166:167], 1.0 op_sel_hi:[1,0]
	v_rcp_f32_e32 v160, v160
	v_rcp_f32_e32 v161, v161
	v_rcp_f32_e32 v162, v162
	v_rcp_f32_e32 v163, v163
	v_rcp_f32_e32 v164, v164
	v_rcp_f32_e32 v165, v165
	v_rcp_f32_e32 v166, v166
	v_rcp_f32_e32 v167, v167
	v_pk_mul_f32 v[160:161], v[44:45], v[160:161]
	v_pk_mul_f32 v[162:163], v[46:47], v[162:163]
	v_pk_mul_f32 v[164:165], v[36:37], v[164:165]
	v_pk_mul_f32 v[166:167], v[38:39], v[166:167]
	v_pk_mul_f32 v[160:161], v[40:41], v[160:161]
	v_pk_mul_f32 v[162:163], v[42:43], v[162:163]
	v_pk_mul_f32 v[164:165], v[32:33], v[164:165]
	v_pk_mul_f32 v[166:167], v[34:35], v[166:167]
	v_cvt_pk_bf16_f32 v172, v160, v161
	v_cvt_pk_bf16_f32 v173, v162, v163
	v_cvt_pk_bf16_f32 v174, v164, v165
	v_cvt_pk_bf16_f32 v175, v166, v167
	global_store_dwordx2 v[158:159], v[172:173], off
	global_store_dwordx2 v[158:159], v[174:175], off offset:128
	v_pk_mul_f32 v[28:29], v[28:29], v[252:253] op_sel_hi:[1,0]
	v_pk_mul_f32 v[30:31], v[30:31], v[252:253] op_sel_hi:[1,0]
	v_pk_mul_f32 v[20:21], v[20:21], v[252:253] op_sel_hi:[1,0]
	v_pk_mul_f32 v[22:23], v[22:23], v[252:253] op_sel_hi:[1,0]
	v_pk_mul_f32 v[24:25], v[24:25], v[252:253] op_sel_hi:[1,0]
	v_pk_mul_f32 v[26:27], v[26:27], v[252:253] op_sel_hi:[1,0]
	v_pk_mul_f32 v[16:17], v[16:17], v[252:253] op_sel_hi:[1,0]
	v_pk_mul_f32 v[18:19], v[18:19], v[252:253] op_sel_hi:[1,0]
	v_add_u32_e32 v141, 0xa0, v140
	v_pk_mul_f32 v[160:161], v[28:29], v[176:177] op_sel_hi:[1,0]
	v_pk_mul_f32 v[162:163], v[30:31], v[176:177] op_sel_hi:[1,0]
	v_pk_mul_f32 v[164:165], v[20:21], v[176:177] op_sel_hi:[1,0]
	v_pk_mul_f32 v[166:167], v[22:23], v[176:177] op_sel_hi:[1,0]
	v_mad_i64_i32 v[204:205], s[2:3], v141, s78, v[138:139]
	v_exp_f32_e32 v160, v160
	v_exp_f32_e32 v161, v161
	v_exp_f32_e32 v162, v162
	v_exp_f32_e32 v163, v163
	v_exp_f32_e32 v164, v164
	v_exp_f32_e32 v165, v165
	v_exp_f32_e32 v166, v166
	v_exp_f32_e32 v167, v167
	v_pk_add_f32 v[160:161], v[160:161], 1.0 op_sel_hi:[1,0]
	v_pk_add_f32 v[162:163], v[162:163], 1.0 op_sel_hi:[1,0]
	v_pk_add_f32 v[164:165], v[164:165], 1.0 op_sel_hi:[1,0]
	v_pk_add_f32 v[166:167], v[166:167], 1.0 op_sel_hi:[1,0]
	v_rcp_f32_e32 v160, v160
	v_rcp_f32_e32 v161, v161
	v_rcp_f32_e32 v162, v162
	v_rcp_f32_e32 v163, v163
	v_rcp_f32_e32 v164, v164
	v_rcp_f32_e32 v165, v165
	v_rcp_f32_e32 v166, v166
	v_rcp_f32_e32 v167, v167
	v_pk_mul_f32 v[160:161], v[28:29], v[160:161]
	v_pk_mul_f32 v[162:163], v[30:31], v[162:163]
	v_pk_mul_f32 v[164:165], v[20:21], v[164:165]
	v_pk_mul_f32 v[166:167], v[22:23], v[166:167]
	v_pk_mul_f32 v[160:161], v[24:25], v[160:161]
	v_pk_mul_f32 v[162:163], v[26:27], v[162:163]
	v_pk_mul_f32 v[164:165], v[16:17], v[164:165]
	v_pk_mul_f32 v[166:167], v[18:19], v[166:167]
	v_cvt_pk_bf16_f32 v168, v160, v161
	v_cvt_pk_bf16_f32 v169, v162, v163
	v_cvt_pk_bf16_f32 v170, v164, v165
	v_cvt_pk_bf16_f32 v171, v166, v167
	global_store_dwordx2 v[204:205], v[168:169], off
	global_store_dwordx2 v[204:205], v[170:171], off offset:128
	v_pk_mul_f32 v[12:13], v[12:13], v[252:253] op_sel:[0,1] op_sel_hi:[1,1]
	v_pk_mul_f32 v[14:15], v[14:15], v[252:253] op_sel:[0,1] op_sel_hi:[1,1]
	v_pk_mul_f32 v[4:5], v[4:5], v[252:253] op_sel:[0,1] op_sel_hi:[1,1]
	v_pk_mul_f32 v[6:7], v[6:7], v[252:253] op_sel:[0,1] op_sel_hi:[1,1]
	v_pk_mul_f32 v[8:9], v[8:9], v[252:253] op_sel:[0,1] op_sel_hi:[1,1]
	v_pk_mul_f32 v[10:11], v[10:11], v[252:253] op_sel:[0,1] op_sel_hi:[1,1]
	v_pk_mul_f32 v[0:1], v[0:1], v[252:253] op_sel:[0,1] op_sel_hi:[1,1]
	v_pk_mul_f32 v[2:3], v[2:3], v[252:253] op_sel:[0,1] op_sel_hi:[1,1]
	v_add_u32_e32 v141, 0xb0, v140
	v_pk_mul_f32 v[160:161], v[12:13], v[176:177] op_sel_hi:[1,0]
	v_pk_mul_f32 v[162:163], v[14:15], v[176:177] op_sel_hi:[1,0]
	v_pk_mul_f32 v[164:165], v[4:5], v[176:177] op_sel_hi:[1,0]
	v_pk_mul_f32 v[166:167], v[6:7], v[176:177] op_sel_hi:[1,0]
	v_mad_i64_i32 v[206:207], s[2:3], v141, s78, v[138:139]
	v_exp_f32_e32 v160, v160
	v_exp_f32_e32 v161, v161
	v_exp_f32_e32 v162, v162
	v_exp_f32_e32 v163, v163
	v_exp_f32_e32 v164, v164
	v_exp_f32_e32 v165, v165
	v_exp_f32_e32 v166, v166
	v_exp_f32_e32 v167, v167
	v_pk_add_f32 v[160:161], v[160:161], 1.0 op_sel_hi:[1,0]
	v_pk_add_f32 v[162:163], v[162:163], 1.0 op_sel_hi:[1,0]
	v_pk_add_f32 v[164:165], v[164:165], 1.0 op_sel_hi:[1,0]
	v_pk_add_f32 v[166:167], v[166:167], 1.0 op_sel_hi:[1,0]
	v_rcp_f32_e32 v160, v160
	v_rcp_f32_e32 v161, v161
	v_rcp_f32_e32 v162, v162
	v_rcp_f32_e32 v163, v163
	v_rcp_f32_e32 v164, v164
	v_rcp_f32_e32 v165, v165
	v_rcp_f32_e32 v166, v166
	v_rcp_f32_e32 v167, v167
	v_pk_mul_f32 v[160:161], v[12:13], v[160:161]
	v_pk_mul_f32 v[162:163], v[14:15], v[162:163]
	v_pk_mul_f32 v[164:165], v[4:5], v[164:165]
	v_pk_mul_f32 v[166:167], v[6:7], v[166:167]
	v_pk_mul_f32 v[160:161], v[8:9], v[160:161]
	v_pk_mul_f32 v[162:163], v[10:11], v[162:163]
	v_pk_mul_f32 v[164:165], v[0:1], v[164:165]
	v_pk_mul_f32 v[166:167], v[2:3], v[166:167]
	v_cvt_pk_bf16_f32 v172, v160, v161
	v_cvt_pk_bf16_f32 v173, v162, v163
	v_cvt_pk_bf16_f32 v174, v164, v165
	v_cvt_pk_bf16_f32 v175, v166, v167
	global_store_dwordx2 v[206:207], v[172:173], off
	global_store_dwordx2 v[206:207], v[174:175], off offset:128
	s_waitcnt vmcnt(16)
	v_add_f32_e32 v208, v209, v208
	v_add_f32_e32 v212, v213, v212
	v_add_f32_e32 v216, v217, v216
	v_add_f32_e32 v220, v221, v220
	v_add_f32_e32 v224, v225, v224
	v_add_f32_e32 v228, v229, v228
	v_add_f32_e32 v232, v233, v232
	v_add_f32_e32 v236, v237, v236
	v_add_f32_e32 v210, v210, v211
	v_add_f32_e32 v214, v214, v215
	v_add_f32_e32 v218, v218, v219
	v_add_f32_e32 v222, v222, v223
	v_add_f32_e32 v226, v226, v227
	v_add_f32_e32 v230, v230, v231
	v_add_f32_e32 v234, v234, v235
	v_add_f32_e32 v238, v238, v239
	v_add_f32_e32 v208, v208, v210
	v_add_f32_e32 v212, v212, v214
	v_add_f32_e32 v216, v216, v218
	v_add_f32_e32 v220, v220, v222
	v_add_f32_e32 v224, v224, v226
	v_add_f32_e32 v228, v228, v230
	v_add_f32_e32 v232, v232, v234
	v_add_f32_e32 v236, v236, v238
	v_fmamk_f32 v208, v208, 0x3a800000, v184
	v_fmamk_f32 v212, v212, 0x3a800000, v184
	v_fmamk_f32 v216, v216, 0x3a800000, v184
	v_fmamk_f32 v220, v220, 0x3a800000, v184
	v_fmamk_f32 v224, v224, 0x3a800000, v184
	v_fmamk_f32 v228, v228, 0x3a800000, v184
	v_fmamk_f32 v232, v232, 0x3a800000, v184
	v_fmamk_f32 v236, v236, 0x3a800000, v184
	v_rsq_f32_e32 v246, v208
	v_rsq_f32_e32 v247, v212
	v_rsq_f32_e32 v248, v216
	v_rsq_f32_e32 v249, v220
	v_rsq_f32_e32 v250, v224
	v_rsq_f32_e32 v251, v228
	v_rsq_f32_e32 v252, v232
	v_rsq_f32_e32 v253, v236
	s_mov_b64 s[2:3], -1
	s_andn2_b64 vcc, exec, s[38:39]
	s_cbranch_vccnz .LBB0_1301
	s_andn2_b64 vcc, exec, s[40:41]
	s_cbranch_vccnz .LBB0_1300
	s_barrier
	s_branch .LBB0_1300
